# previous stack + GEMM unit loops: accumulator zeroing (127 v_mov per unit) replaced by peeled first K trip with SrcC=0 MFMAs (6 GEMM instances)
# speedup vs baseline: 1.0109x; 1.0037x over previous
.LBB0_205:
	s_lshl_b32 s16, s46, 8
	s_ashr_i32 s17, s16, 31
	s_lshl_b64 s[16:17], s[16:17], 11
	s_add_u32 s16, s2, s16
	s_addc_u32 s17, s3, s17
	s_and_b64 s[18:19], s[4:5], exec
	s_cselect_b32 s7, s17, s21
	s_cselect_b32 s48, s16, s20
	s_ashr_i32 s15, s14, 31
	s_lshl_b64 s[18:19], s[14:15], 19
	s_add_u32 s18, s22, s18
	s_addc_u32 s19, s30, s19
	s_and_b64 s[26:27], s[4:5], exec
	s_cselect_b32 s15, s19, s25
	s_cselect_b32 s49, s18, s24
	s_add_u32 s50, s24, 0x100
	v_mov_b32_e32 v34, 0
	s_addc_u32 s51, s25, 0
	s_mov_b32 s52, -2
	s_add_u32 s24, s20, 0x100
	s_addc_u32 s25, s21, 0
	s_cmp_eq_u32 s52, 12
	s_cselect_b32 s29, s7, s25
	s_cselect_b32 s28, s48, s24
	s_cselect_b32 s27, s15, s51
	s_cselect_b32 s26, s49, s50
	s_add_i32 s23, 0, 0x10000
	v_add_u32_e32 v144, s23, v146
	s_add_i32 s53, 0, 0x14000
	ds_read_b128 v[148:151], v144
	ds_read_b128 v[152:155], v144 offset:1024
	ds_read_b128 v[156:159], v144 offset:2048
	ds_read_b128 v[160:163], v144 offset:3072
	v_add_u32_e32 v144, s53, v146
	ds_read_b128 v[164:167], v144
	ds_read_b128 v[168:171], v144 offset:1024
	ds_read_b128 v[172:175], v144 offset:2048
	ds_read_b128 v[176:179], v144 offset:3072
	v_lshl_add_u64 v[144:145], s[20:21], 0, v[142:143]
	s_add_i32 m0, s35, 0xc000
	ds_read_b128 v[180:183], v147
	ds_read_b128 v[184:187], v147 offset:1024
	ds_read_b128 v[188:191], v147 offset:2048
	ds_read_b128 v[192:195], v147 offset:3072
	ds_read_b128 v[196:199], v147 offset:4096
	ds_read_b128 v[200:203], v147 offset:5120
	ds_read_b128 v[204:207], v147 offset:6144
	ds_read_b128 v[208:211], v147 offset:7168
	global_load_lds_dwordx4 v[144:145], off
	v_lshl_add_u64 v[144:145], s[20:21], 0, v[140:141]
	s_add_i32 m0, s35, 0xe000
	s_nop 0
	global_load_lds_dwordx4 v[144:145], off
	s_waitcnt vmcnt(8)
	s_waitcnt lgkmcnt(0)
	s_barrier
	s_setprio 1
	s_waitcnt lgkmcnt(0)
	v_mfma_f32_16x16x32_bf16 v[126:129], v[148:151], v[180:183], 0
	v_mfma_f32_16x16x32_bf16 v[122:125], v[156:159], v[180:183], 0
	v_mfma_f32_16x16x32_bf16 v[110:113], v[148:151], v[188:191], 0
	v_mfma_f32_16x16x32_bf16 v[106:109], v[156:159], v[188:191], 0
	v_mfma_f32_16x16x32_bf16 v[94:97], v[148:151], v[196:199], 0
	v_mfma_f32_16x16x32_bf16 v[90:93], v[156:159], v[196:199], 0
	v_mfma_f32_16x16x32_bf16 v[78:81], v[148:151], v[204:207], 0
	v_mfma_f32_16x16x32_bf16 v[74:77], v[156:159], v[204:207], 0
	v_mfma_f32_16x16x32_bf16 v[126:129], v[152:155], v[184:187], v[126:129]
	v_mfma_f32_16x16x32_bf16 v[122:125], v[160:163], v[184:187], v[122:125]
	v_mfma_f32_16x16x32_bf16 v[110:113], v[152:155], v[192:195], v[110:113]
	v_mfma_f32_16x16x32_bf16 v[106:109], v[160:163], v[192:195], v[106:109]
	v_mfma_f32_16x16x32_bf16 v[94:97], v[152:155], v[200:203], v[94:97]
	v_mfma_f32_16x16x32_bf16 v[90:93], v[160:163], v[200:203], v[90:93]
	v_mfma_f32_16x16x32_bf16 v[78:81], v[152:155], v[208:211], v[78:81]
	v_mfma_f32_16x16x32_bf16 v[74:77], v[160:163], v[208:211], v[74:77]
	s_setprio 0
	s_setprio 1
	v_mfma_f32_16x16x32_bf16 v[118:121], v[164:167], v[180:183], 0
	v_mfma_f32_16x16x32_bf16 v[114:117], v[172:175], v[180:183], 0
	v_mfma_f32_16x16x32_bf16 v[102:105], v[164:167], v[188:191], 0
	v_mfma_f32_16x16x32_bf16 v[98:101], v[172:175], v[188:191], 0
	v_mfma_f32_16x16x32_bf16 v[86:89], v[164:167], v[196:199], 0
	v_mfma_f32_16x16x32_bf16 v[82:85], v[172:175], v[196:199], 0
	v_mfma_f32_16x16x32_bf16 v[70:73], v[164:167], v[204:207], 0
	v_mfma_f32_16x16x32_bf16 v[66:69], v[172:175], v[204:207], 0
	v_mfma_f32_16x16x32_bf16 v[118:121], v[168:171], v[184:187], v[118:121]
	v_mfma_f32_16x16x32_bf16 v[114:117], v[176:179], v[184:187], v[114:117]
	v_mfma_f32_16x16x32_bf16 v[102:105], v[168:171], v[192:195], v[102:105]
	v_mfma_f32_16x16x32_bf16 v[98:101], v[176:179], v[192:195], v[98:101]
	v_mfma_f32_16x16x32_bf16 v[86:89], v[168:171], v[200:203], v[86:89]
	v_mfma_f32_16x16x32_bf16 v[82:85], v[176:179], v[200:203], v[82:85]
	v_mfma_f32_16x16x32_bf16 v[70:73], v[168:171], v[208:211], v[70:73]
	v_mfma_f32_16x16x32_bf16 v[66:69], v[176:179], v[208:211], v[66:69]
	s_setprio 0
	s_barrier
	s_add_i32 s20, s23, s31
	v_lshl_add_u64 v[144:145], s[26:27], 0, v[0:1]
	s_mov_b32 m0, s20
	ds_read_b128 v[180:183], v147 offset:16384
	ds_read_b128 v[184:187], v147 offset:17408
	ds_read_b128 v[188:191], v147 offset:18432
	ds_read_b128 v[192:195], v147 offset:19456
	ds_read_b128 v[196:199], v147 offset:20480
	ds_read_b128 v[200:203], v147 offset:21504
	ds_read_b128 v[204:207], v147 offset:22528
	ds_read_b128 v[208:211], v147 offset:23552
	global_load_lds_dwordx4 v[144:145], off
	s_add_i32 m0, s20, 0x2000
	s_add_u32 s20, s26, 0x40000
	v_lshl_add_u64 v[212:213], s[26:27], 0, v[130:131]
	s_addc_u32 s21, s27, 0
	s_add_i32 s23, s53, s31
	global_load_lds_dwordx4 v[212:213], off
	v_lshl_add_u64 v[214:215], s[20:21], 0, v[0:1]
	s_mov_b32 m0, s23
	v_lshl_add_u64 v[216:217], s[28:29], 0, v[134:135]
	global_load_lds_dwordx4 v[214:215], off
	v_lshl_add_u64 v[214:215], s[20:21], 0, v[130:131]
	s_add_i32 m0, s23, 0x2000
	s_nop 0
	global_load_lds_dwordx4 v[214:215], off
	v_lshl_add_u64 v[214:215], s[28:29], 0, v[132:133]
	s_mov_b32 m0, s35
	s_nop 0
	global_load_lds_dwordx4 v[214:215], off
	s_mov_b32 m0, s36
	s_nop 0
	global_load_lds_dwordx4 v[216:217], off
	s_waitcnt vmcnt(8)
	s_waitcnt lgkmcnt(0)
	s_barrier
	s_setprio 1
	s_waitcnt lgkmcnt(0)
	v_mfma_f32_16x16x32_bf16 v[62:65], v[148:151], v[180:183], 0
	v_mfma_f32_16x16x32_bf16 v[58:61], v[156:159], v[180:183], 0
	v_mfma_f32_16x16x32_bf16 v[46:49], v[148:151], v[188:191], 0
	v_mfma_f32_16x16x32_bf16 v[42:45], v[156:159], v[188:191], 0
	v_mfma_f32_16x16x32_bf16 v[22:25], v[148:151], v[196:199], 0
	v_mfma_f32_16x16x32_bf16 v[18:21], v[156:159], v[196:199], 0
	v_mfma_f32_16x16x32_bf16 v[6:9], v[148:151], v[204:207], 0
	v_mfma_f32_16x16x32_bf16 v[2:5], v[156:159], v[204:207], 0
	v_mfma_f32_16x16x32_bf16 v[62:65], v[152:155], v[184:187], v[62:65]
	v_mfma_f32_16x16x32_bf16 v[58:61], v[160:163], v[184:187], v[58:61]
	v_mfma_f32_16x16x32_bf16 v[46:49], v[152:155], v[192:195], v[46:49]
	v_mfma_f32_16x16x32_bf16 v[42:45], v[160:163], v[192:195], v[42:45]
	v_mfma_f32_16x16x32_bf16 v[22:25], v[152:155], v[200:203], v[22:25]
	v_mfma_f32_16x16x32_bf16 v[18:21], v[160:163], v[200:203], v[18:21]
	v_mfma_f32_16x16x32_bf16 v[6:9], v[152:155], v[208:211], v[6:9]
	v_mfma_f32_16x16x32_bf16 v[2:5], v[160:163], v[208:211], v[2:5]
	s_setprio 0
	s_setprio 1
	v_mfma_f32_16x16x32_bf16 v[54:57], v[164:167], v[180:183], 0
	v_mfma_f32_16x16x32_bf16 v[50:53], v[172:175], v[180:183], 0
	v_mfma_f32_16x16x32_bf16 v[38:41], v[164:167], v[188:191], 0
	v_mfma_f32_16x16x32_bf16 v[34:37], v[172:175], v[188:191], 0
	v_mfma_f32_16x16x32_bf16 v[26:29], v[164:167], v[196:199], 0
	v_mfma_f32_16x16x32_bf16 v[30:33], v[172:175], v[196:199], 0
	v_mfma_f32_16x16x32_bf16 v[10:13], v[164:167], v[204:207], 0
	v_mfma_f32_16x16x32_bf16 v[14:17], v[172:175], v[204:207], 0
	v_mfma_f32_16x16x32_bf16 v[54:57], v[168:171], v[184:187], v[54:57]
	v_mfma_f32_16x16x32_bf16 v[50:53], v[176:179], v[184:187], v[50:53]
	v_mfma_f32_16x16x32_bf16 v[38:41], v[168:171], v[192:195], v[38:41]
	v_mfma_f32_16x16x32_bf16 v[34:37], v[176:179], v[192:195], v[34:37]
	v_mfma_f32_16x16x32_bf16 v[26:29], v[168:171], v[200:203], v[26:29]
	v_mfma_f32_16x16x32_bf16 v[30:33], v[176:179], v[200:203], v[30:33]
	v_mfma_f32_16x16x32_bf16 v[10:13], v[168:171], v[208:211], v[10:13]
	v_mfma_f32_16x16x32_bf16 v[14:17], v[176:179], v[208:211], v[14:17]
	s_setprio 0
	s_barrier
	s_add_i32 s20, 0, 0x18000
	s_add_i32 s23, 0, 0x1c000
	v_add_u32_e32 v160, s20, v146
	v_add_u32_e32 v176, s23, v146
	ds_read_b128 v[148:151], v160
	ds_read_b128 v[152:155], v160 offset:1024
	ds_read_b128 v[156:159], v160 offset:2048
	ds_read_b128 v[160:163], v160 offset:3072
	ds_read_b128 v[164:167], v176
	ds_read_b128 v[168:171], v176 offset:1024
	ds_read_b128 v[172:175], v176 offset:2048
	ds_read_b128 v[176:179], v176 offset:3072
	s_mov_b32 m0, s37
	v_lshl_add_u64 v[218:219], s[28:29], 0, v[136:137]
	ds_read_b128 v[180:183], v147 offset:32768
	ds_read_b128 v[184:187], v147 offset:33792
	ds_read_b128 v[188:191], v147 offset:34816
	ds_read_b128 v[192:195], v147 offset:35840
	ds_read_b128 v[196:199], v147 offset:36864
	ds_read_b128 v[200:203], v147 offset:37888
	ds_read_b128 v[204:207], v147 offset:38912
	ds_read_b128 v[208:211], v147 offset:39936
	global_load_lds_dwordx4 v[218:219], off
	v_lshl_add_u64 v[218:219], s[28:29], 0, v[138:139]
	s_mov_b32 m0, s38
	s_nop 0
	global_load_lds_dwordx4 v[218:219], off
	s_waitcnt vmcnt(8)
	s_waitcnt lgkmcnt(0)
	s_barrier
	s_setprio 1
	s_waitcnt lgkmcnt(0)
	v_mfma_f32_16x16x32_bf16 v[126:129], v[148:151], v[180:183], v[126:129]
	v_mfma_f32_16x16x32_bf16 v[122:125], v[156:159], v[180:183], v[122:125]
	v_mfma_f32_16x16x32_bf16 v[110:113], v[148:151], v[188:191], v[110:113]
	v_mfma_f32_16x16x32_bf16 v[106:109], v[156:159], v[188:191], v[106:109]
	v_mfma_f32_16x16x32_bf16 v[94:97], v[148:151], v[196:199], v[94:97]
	v_mfma_f32_16x16x32_bf16 v[90:93], v[156:159], v[196:199], v[90:93]
	v_mfma_f32_16x16x32_bf16 v[78:81], v[148:151], v[204:207], v[78:81]
	v_mfma_f32_16x16x32_bf16 v[74:77], v[156:159], v[204:207], v[74:77]
	v_mfma_f32_16x16x32_bf16 v[126:129], v[152:155], v[184:187], v[126:129]
	v_mfma_f32_16x16x32_bf16 v[122:125], v[160:163], v[184:187], v[122:125]
	v_mfma_f32_16x16x32_bf16 v[110:113], v[152:155], v[192:195], v[110:113]
	v_mfma_f32_16x16x32_bf16 v[106:109], v[160:163], v[192:195], v[106:109]
	v_mfma_f32_16x16x32_bf16 v[94:97], v[152:155], v[200:203], v[94:97]
	v_mfma_f32_16x16x32_bf16 v[90:93], v[160:163], v[200:203], v[90:93]
	v_mfma_f32_16x16x32_bf16 v[78:81], v[152:155], v[208:211], v[78:81]
	v_mfma_f32_16x16x32_bf16 v[74:77], v[160:163], v[208:211], v[74:77]
	s_setprio 0
	s_setprio 1
	v_mfma_f32_16x16x32_bf16 v[118:121], v[164:167], v[180:183], v[118:121]
	v_mfma_f32_16x16x32_bf16 v[114:117], v[172:175], v[180:183], v[114:117]
	v_mfma_f32_16x16x32_bf16 v[102:105], v[164:167], v[188:191], v[102:105]
	v_mfma_f32_16x16x32_bf16 v[98:101], v[172:175], v[188:191], v[98:101]
	v_mfma_f32_16x16x32_bf16 v[86:89], v[164:167], v[196:199], v[86:89]
	v_mfma_f32_16x16x32_bf16 v[82:85], v[172:175], v[196:199], v[82:85]
	v_mfma_f32_16x16x32_bf16 v[70:73], v[164:167], v[204:207], v[70:73]
	v_mfma_f32_16x16x32_bf16 v[66:69], v[172:175], v[204:207], v[66:69]
	v_mfma_f32_16x16x32_bf16 v[118:121], v[168:171], v[184:187], v[118:121]
	v_mfma_f32_16x16x32_bf16 v[114:117], v[176:179], v[184:187], v[114:117]
	v_mfma_f32_16x16x32_bf16 v[102:105], v[168:171], v[192:195], v[102:105]
	v_mfma_f32_16x16x32_bf16 v[98:101], v[176:179], v[192:195], v[98:101]
	v_mfma_f32_16x16x32_bf16 v[86:89], v[168:171], v[200:203], v[86:89]
	v_mfma_f32_16x16x32_bf16 v[82:85], v[176:179], v[200:203], v[82:85]
	v_mfma_f32_16x16x32_bf16 v[70:73], v[168:171], v[208:211], v[70:73]
	v_mfma_f32_16x16x32_bf16 v[66:69], v[176:179], v[208:211], v[66:69]
	s_setprio 0
	s_barrier
	s_add_i32 s20, s20, s31
	v_lshl_add_u64 v[144:145], v[144:145], 0, s[82:83]
	s_mov_b32 m0, s20
	ds_read_b128 v[180:183], v147 offset:49152
	ds_read_b128 v[184:187], v147 offset:50176
	ds_read_b128 v[188:191], v147 offset:51200
	ds_read_b128 v[192:195], v147 offset:52224
	ds_read_b128 v[196:199], v147 offset:53248
	ds_read_b128 v[200:203], v147 offset:54272
	ds_read_b128 v[204:207], v147 offset:55296
	ds_read_b128 v[208:211], v147 offset:56320
	global_load_lds_dwordx4 v[144:145], off
	s_add_i32 m0, s20, 0x2000
	s_add_u32 s20, s26, 0x40080
	v_lshl_add_u64 v[144:145], v[212:213], 0, s[82:83]
	s_addc_u32 s21, s27, 0
	s_add_i32 s23, s23, s31
	global_load_lds_dwordx4 v[144:145], off
	v_lshl_add_u64 v[144:145], s[20:21], 0, v[0:1]
	s_mov_b32 m0, s23
	s_nop 0
	global_load_lds_dwordx4 v[144:145], off
	v_lshl_add_u64 v[144:145], s[20:21], 0, v[130:131]
	s_add_i32 m0, s23, 0x2000
	s_nop 0
	global_load_lds_dwordx4 v[144:145], off
	v_lshl_add_u64 v[144:145], v[214:215], 0, s[82:83]
	s_mov_b32 m0, s41
	s_nop 0
	global_load_lds_dwordx4 v[144:145], off
	v_lshl_add_u64 v[144:145], v[216:217], 0, s[82:83]
	s_mov_b32 m0, s42
	s_nop 0
	global_load_lds_dwordx4 v[144:145], off
	s_waitcnt vmcnt(8)
	s_waitcnt lgkmcnt(0)
	s_barrier
	s_setprio 1
	s_waitcnt lgkmcnt(0)
	v_mfma_f32_16x16x32_bf16 v[62:65], v[148:151], v[180:183], v[62:65]
	v_mfma_f32_16x16x32_bf16 v[58:61], v[156:159], v[180:183], v[58:61]
	v_mfma_f32_16x16x32_bf16 v[46:49], v[148:151], v[188:191], v[46:49]
	v_mfma_f32_16x16x32_bf16 v[42:45], v[156:159], v[188:191], v[42:45]
	v_mfma_f32_16x16x32_bf16 v[22:25], v[148:151], v[196:199], v[22:25]
	v_mfma_f32_16x16x32_bf16 v[18:21], v[156:159], v[196:199], v[18:21]
	v_mfma_f32_16x16x32_bf16 v[6:9], v[148:151], v[204:207], v[6:9]
	v_mfma_f32_16x16x32_bf16 v[2:5], v[156:159], v[204:207], v[2:5]
	v_mfma_f32_16x16x32_bf16 v[62:65], v[152:155], v[184:187], v[62:65]
	v_mfma_f32_16x16x32_bf16 v[58:61], v[160:163], v[184:187], v[58:61]
	v_mfma_f32_16x16x32_bf16 v[46:49], v[152:155], v[192:195], v[46:49]
	v_mfma_f32_16x16x32_bf16 v[42:45], v[160:163], v[192:195], v[42:45]
	v_mfma_f32_16x16x32_bf16 v[22:25], v[152:155], v[200:203], v[22:25]
	v_mfma_f32_16x16x32_bf16 v[18:21], v[160:163], v[200:203], v[18:21]
	v_mfma_f32_16x16x32_bf16 v[6:9], v[152:155], v[208:211], v[6:9]
	v_mfma_f32_16x16x32_bf16 v[2:5], v[160:163], v[208:211], v[2:5]
	s_setprio 0
	s_setprio 1
	v_mfma_f32_16x16x32_bf16 v[54:57], v[164:167], v[180:183], v[54:57]
	v_mfma_f32_16x16x32_bf16 v[50:53], v[172:175], v[180:183], v[50:53]
	v_mfma_f32_16x16x32_bf16 v[38:41], v[164:167], v[188:191], v[38:41]
	v_mfma_f32_16x16x32_bf16 v[34:37], v[172:175], v[188:191], v[34:37]
	v_mfma_f32_16x16x32_bf16 v[26:29], v[164:167], v[196:199], v[26:29]
	v_mfma_f32_16x16x32_bf16 v[30:33], v[172:175], v[196:199], v[30:33]
	v_mfma_f32_16x16x32_bf16 v[10:13], v[164:167], v[204:207], v[10:13]
	v_mfma_f32_16x16x32_bf16 v[14:17], v[172:175], v[204:207], v[14:17]
	v_mfma_f32_16x16x32_bf16 v[54:57], v[168:171], v[184:187], v[54:57]
	v_mfma_f32_16x16x32_bf16 v[50:53], v[176:179], v[184:187], v[50:53]
	v_mfma_f32_16x16x32_bf16 v[38:41], v[168:171], v[192:195], v[38:41]
	v_mfma_f32_16x16x32_bf16 v[34:37], v[176:179], v[192:195], v[34:37]
	v_mfma_f32_16x16x32_bf16 v[26:29], v[168:171], v[200:203], v[26:29]
	v_mfma_f32_16x16x32_bf16 v[30:33], v[176:179], v[200:203], v[30:33]
	v_mfma_f32_16x16x32_bf16 v[10:13], v[168:171], v[208:211], v[10:13]
	v_mfma_f32_16x16x32_bf16 v[14:17], v[176:179], v[208:211], v[14:17]
	s_setprio 0
	s_barrier
	s_branch .Lpeel_latch_206

.Lpeel_latch_206:
	s_add_i32 s52, s52, 2
	s_add_u32 s50, s50, 0x100
	s_addc_u32 s51, s51, 0
	s_cmp_gt_u32 s52, 13
	s_mov_b64 s[20:21], s[24:25]
	s_cbranch_scc0 .LBB0_206
	s_and_b64 vcc, exec, s[12:13]
	s_cbranch_vccz .LBB0_209
	s_barrier

.LBB0_263:
	s_lshl_b32 s16, s42, 8
	s_ashr_i32 s17, s16, 31
	s_lshl_b64 s[16:17], s[16:17], 11
	s_add_u32 s16, s2, s16
	s_addc_u32 s17, s3, s17
	s_and_b64 s[18:19], s[14:15], exec
	s_cselect_b32 s5, s17, s21
	s_cselect_b32 s44, s16, s20
	s_ashr_i32 s13, s12, 31
	s_lshl_b64 s[18:19], s[12:13], 19
	s_add_u32 s18, s22, s18
	s_addc_u32 s19, s30, s19
	s_and_b64 s[26:27], s[14:15], exec
	s_cselect_b32 s13, s19, s25
	s_cselect_b32 s45, s18, s24
	s_add_u32 s46, s24, 0x100
	v_mov_b32_e32 v34, 0
	s_addc_u32 s47, s25, 0
	s_mov_b32 s48, -2
	s_add_u32 s24, s20, 0x100
	s_addc_u32 s25, s21, 0
	s_cmp_eq_u32 s48, 12
	s_cselect_b32 s29, s5, s25
	s_cselect_b32 s28, s44, s24
	s_cselect_b32 s27, s13, s47
	s_cselect_b32 s26, s45, s46
	s_add_i32 s23, 0, 0x10000
	v_add_u32_e32 v144, s23, v146
	s_add_i32 s49, 0, 0x14000
	ds_read_b128 v[148:151], v144
	ds_read_b128 v[152:155], v144 offset:1024
	ds_read_b128 v[156:159], v144 offset:2048
	ds_read_b128 v[160:163], v144 offset:3072
	v_add_u32_e32 v144, s49, v146
	ds_read_b128 v[164:167], v144
	ds_read_b128 v[168:171], v144 offset:1024
	ds_read_b128 v[172:175], v144 offset:2048
	ds_read_b128 v[176:179], v144 offset:3072
	v_lshl_add_u64 v[144:145], s[20:21], 0, v[142:143]
	s_add_i32 m0, s35, 0xc000
	ds_read_b128 v[180:183], v147
	ds_read_b128 v[184:187], v147 offset:1024
	ds_read_b128 v[188:191], v147 offset:2048
	ds_read_b128 v[192:195], v147 offset:3072
	ds_read_b128 v[196:199], v147 offset:4096
	ds_read_b128 v[200:203], v147 offset:5120
	ds_read_b128 v[204:207], v147 offset:6144
	ds_read_b128 v[208:211], v147 offset:7168
	global_load_lds_dwordx4 v[144:145], off
	v_lshl_add_u64 v[144:145], s[20:21], 0, v[140:141]
	s_add_i32 m0, s35, 0xe000
	s_nop 0
	global_load_lds_dwordx4 v[144:145], off
	s_waitcnt vmcnt(8)
	s_waitcnt lgkmcnt(0)
	s_barrier
	s_setprio 1
	s_waitcnt lgkmcnt(0)
	v_mfma_f32_16x16x32_bf16 v[126:129], v[148:151], v[180:183], 0
	v_mfma_f32_16x16x32_bf16 v[122:125], v[156:159], v[180:183], 0
	v_mfma_f32_16x16x32_bf16 v[110:113], v[148:151], v[188:191], 0
	v_mfma_f32_16x16x32_bf16 v[106:109], v[156:159], v[188:191], 0
	v_mfma_f32_16x16x32_bf16 v[94:97], v[148:151], v[196:199], 0
	v_mfma_f32_16x16x32_bf16 v[90:93], v[156:159], v[196:199], 0
	v_mfma_f32_16x16x32_bf16 v[78:81], v[148:151], v[204:207], 0
	v_mfma_f32_16x16x32_bf16 v[74:77], v[156:159], v[204:207], 0
	v_mfma_f32_16x16x32_bf16 v[126:129], v[152:155], v[184:187], v[126:129]
	v_mfma_f32_16x16x32_bf16 v[122:125], v[160:163], v[184:187], v[122:125]
	v_mfma_f32_16x16x32_bf16 v[110:113], v[152:155], v[192:195], v[110:113]
	v_mfma_f32_16x16x32_bf16 v[106:109], v[160:163], v[192:195], v[106:109]
	v_mfma_f32_16x16x32_bf16 v[94:97], v[152:155], v[200:203], v[94:97]
	v_mfma_f32_16x16x32_bf16 v[90:93], v[160:163], v[200:203], v[90:93]
	v_mfma_f32_16x16x32_bf16 v[78:81], v[152:155], v[208:211], v[78:81]
	v_mfma_f32_16x16x32_bf16 v[74:77], v[160:163], v[208:211], v[74:77]
	s_setprio 0
	s_setprio 1
	v_mfma_f32_16x16x32_bf16 v[118:121], v[164:167], v[180:183], 0
	v_mfma_f32_16x16x32_bf16 v[114:117], v[172:175], v[180:183], 0
	v_mfma_f32_16x16x32_bf16 v[102:105], v[164:167], v[188:191], 0
	v_mfma_f32_16x16x32_bf16 v[98:101], v[172:175], v[188:191], 0
	v_mfma_f32_16x16x32_bf16 v[86:89], v[164:167], v[196:199], 0
	v_mfma_f32_16x16x32_bf16 v[82:85], v[172:175], v[196:199], 0
	v_mfma_f32_16x16x32_bf16 v[70:73], v[164:167], v[204:207], 0
	v_mfma_f32_16x16x32_bf16 v[66:69], v[172:175], v[204:207], 0
	v_mfma_f32_16x16x32_bf16 v[118:121], v[168:171], v[184:187], v[118:121]
	v_mfma_f32_16x16x32_bf16 v[114:117], v[176:179], v[184:187], v[114:117]
	v_mfma_f32_16x16x32_bf16 v[102:105], v[168:171], v[192:195], v[102:105]
	v_mfma_f32_16x16x32_bf16 v[98:101], v[176:179], v[192:195], v[98:101]
	v_mfma_f32_16x16x32_bf16 v[86:89], v[168:171], v[200:203], v[86:89]
	v_mfma_f32_16x16x32_bf16 v[82:85], v[176:179], v[200:203], v[82:85]
	v_mfma_f32_16x16x32_bf16 v[70:73], v[168:171], v[208:211], v[70:73]
	v_mfma_f32_16x16x32_bf16 v[66:69], v[176:179], v[208:211], v[66:69]
	s_setprio 0
	s_barrier
	s_add_i32 s20, s23, s31
	v_lshl_add_u64 v[144:145], s[26:27], 0, v[0:1]
	s_mov_b32 m0, s20
	ds_read_b128 v[180:183], v147 offset:16384
	ds_read_b128 v[184:187], v147 offset:17408
	ds_read_b128 v[188:191], v147 offset:18432
	ds_read_b128 v[192:195], v147 offset:19456
	ds_read_b128 v[196:199], v147 offset:20480
	ds_read_b128 v[200:203], v147 offset:21504
	ds_read_b128 v[204:207], v147 offset:22528
	ds_read_b128 v[208:211], v147 offset:23552
	global_load_lds_dwordx4 v[144:145], off
	s_add_i32 m0, s20, 0x2000
	s_add_u32 s20, s26, 0x40000
	v_lshl_add_u64 v[212:213], s[26:27], 0, v[130:131]
	s_addc_u32 s21, s27, 0
	s_add_i32 s23, s49, s31
	global_load_lds_dwordx4 v[212:213], off
	v_lshl_add_u64 v[214:215], s[20:21], 0, v[0:1]
	s_mov_b32 m0, s23
	v_lshl_add_u64 v[216:217], s[28:29], 0, v[134:135]
	global_load_lds_dwordx4 v[214:215], off
	v_lshl_add_u64 v[214:215], s[20:21], 0, v[130:131]
	s_add_i32 m0, s23, 0x2000
	s_nop 0
	global_load_lds_dwordx4 v[214:215], off
	v_lshl_add_u64 v[214:215], s[28:29], 0, v[132:133]
	s_mov_b32 m0, s35
	s_nop 0
	global_load_lds_dwordx4 v[214:215], off
	s_mov_b32 m0, s36
	s_nop 0
	global_load_lds_dwordx4 v[216:217], off
	s_waitcnt vmcnt(8)
	s_waitcnt lgkmcnt(0)
	s_barrier
	s_setprio 1
	s_waitcnt lgkmcnt(0)
	v_mfma_f32_16x16x32_bf16 v[62:65], v[148:151], v[180:183], 0
	v_mfma_f32_16x16x32_bf16 v[58:61], v[156:159], v[180:183], 0
	v_mfma_f32_16x16x32_bf16 v[46:49], v[148:151], v[188:191], 0
	v_mfma_f32_16x16x32_bf16 v[42:45], v[156:159], v[188:191], 0
	v_mfma_f32_16x16x32_bf16 v[22:25], v[148:151], v[196:199], 0
	v_mfma_f32_16x16x32_bf16 v[18:21], v[156:159], v[196:199], 0
	v_mfma_f32_16x16x32_bf16 v[6:9], v[148:151], v[204:207], 0
	v_mfma_f32_16x16x32_bf16 v[2:5], v[156:159], v[204:207], 0
	v_mfma_f32_16x16x32_bf16 v[62:65], v[152:155], v[184:187], v[62:65]
	v_mfma_f32_16x16x32_bf16 v[58:61], v[160:163], v[184:187], v[58:61]
	v_mfma_f32_16x16x32_bf16 v[46:49], v[152:155], v[192:195], v[46:49]
	v_mfma_f32_16x16x32_bf16 v[42:45], v[160:163], v[192:195], v[42:45]
	v_mfma_f32_16x16x32_bf16 v[22:25], v[152:155], v[200:203], v[22:25]
	v_mfma_f32_16x16x32_bf16 v[18:21], v[160:163], v[200:203], v[18:21]
	v_mfma_f32_16x16x32_bf16 v[6:9], v[152:155], v[208:211], v[6:9]
	v_mfma_f32_16x16x32_bf16 v[2:5], v[160:163], v[208:211], v[2:5]
	s_setprio 0
	s_setprio 1
	v_mfma_f32_16x16x32_bf16 v[54:57], v[164:167], v[180:183], 0
	v_mfma_f32_16x16x32_bf16 v[50:53], v[172:175], v[180:183], 0
	v_mfma_f32_16x16x32_bf16 v[38:41], v[164:167], v[188:191], 0
	v_mfma_f32_16x16x32_bf16 v[34:37], v[172:175], v[188:191], 0
	v_mfma_f32_16x16x32_bf16 v[26:29], v[164:167], v[196:199], 0
	v_mfma_f32_16x16x32_bf16 v[30:33], v[172:175], v[196:199], 0
	v_mfma_f32_16x16x32_bf16 v[10:13], v[164:167], v[204:207], 0
	v_mfma_f32_16x16x32_bf16 v[14:17], v[172:175], v[204:207], 0
	v_mfma_f32_16x16x32_bf16 v[54:57], v[168:171], v[184:187], v[54:57]
	v_mfma_f32_16x16x32_bf16 v[50:53], v[176:179], v[184:187], v[50:53]
	v_mfma_f32_16x16x32_bf16 v[38:41], v[168:171], v[192:195], v[38:41]
	v_mfma_f32_16x16x32_bf16 v[34:37], v[176:179], v[192:195], v[34:37]
	v_mfma_f32_16x16x32_bf16 v[26:29], v[168:171], v[200:203], v[26:29]
	v_mfma_f32_16x16x32_bf16 v[30:33], v[176:179], v[200:203], v[30:33]
	v_mfma_f32_16x16x32_bf16 v[10:13], v[168:171], v[208:211], v[10:13]
	v_mfma_f32_16x16x32_bf16 v[14:17], v[176:179], v[208:211], v[14:17]
	s_setprio 0
	s_barrier
	s_add_i32 s20, 0, 0x18000
	s_add_i32 s23, 0, 0x1c000
	v_add_u32_e32 v160, s20, v146
	v_add_u32_e32 v176, s23, v146
	ds_read_b128 v[148:151], v160
	ds_read_b128 v[152:155], v160 offset:1024
	ds_read_b128 v[156:159], v160 offset:2048
	ds_read_b128 v[160:163], v160 offset:3072
	ds_read_b128 v[164:167], v176
	ds_read_b128 v[168:171], v176 offset:1024
	ds_read_b128 v[172:175], v176 offset:2048
	ds_read_b128 v[176:179], v176 offset:3072
	s_mov_b32 m0, s37
	v_lshl_add_u64 v[218:219], s[28:29], 0, v[136:137]
	ds_read_b128 v[180:183], v147 offset:32768
	ds_read_b128 v[184:187], v147 offset:33792
	ds_read_b128 v[188:191], v147 offset:34816
	ds_read_b128 v[192:195], v147 offset:35840
	ds_read_b128 v[196:199], v147 offset:36864
	ds_read_b128 v[200:203], v147 offset:37888
	ds_read_b128 v[204:207], v147 offset:38912
	ds_read_b128 v[208:211], v147 offset:39936
	global_load_lds_dwordx4 v[218:219], off
	v_lshl_add_u64 v[218:219], s[28:29], 0, v[138:139]
	s_mov_b32 m0, s38
	s_nop 0
	global_load_lds_dwordx4 v[218:219], off
	s_waitcnt vmcnt(8)
	s_waitcnt lgkmcnt(0)
	s_barrier
	s_setprio 1
	s_waitcnt lgkmcnt(0)
	v_mfma_f32_16x16x32_bf16 v[126:129], v[148:151], v[180:183], v[126:129]
	v_mfma_f32_16x16x32_bf16 v[122:125], v[156:159], v[180:183], v[122:125]
	v_mfma_f32_16x16x32_bf16 v[110:113], v[148:151], v[188:191], v[110:113]
	v_mfma_f32_16x16x32_bf16 v[106:109], v[156:159], v[188:191], v[106:109]
	v_mfma_f32_16x16x32_bf16 v[94:97], v[148:151], v[196:199], v[94:97]
	v_mfma_f32_16x16x32_bf16 v[90:93], v[156:159], v[196:199], v[90:93]
	v_mfma_f32_16x16x32_bf16 v[78:81], v[148:151], v[204:207], v[78:81]
	v_mfma_f32_16x16x32_bf16 v[74:77], v[156:159], v[204:207], v[74:77]
	v_mfma_f32_16x16x32_bf16 v[126:129], v[152:155], v[184:187], v[126:129]
	v_mfma_f32_16x16x32_bf16 v[122:125], v[160:163], v[184:187], v[122:125]
	v_mfma_f32_16x16x32_bf16 v[110:113], v[152:155], v[192:195], v[110:113]
	v_mfma_f32_16x16x32_bf16 v[106:109], v[160:163], v[192:195], v[106:109]
	v_mfma_f32_16x16x32_bf16 v[94:97], v[152:155], v[200:203], v[94:97]
	v_mfma_f32_16x16x32_bf16 v[90:93], v[160:163], v[200:203], v[90:93]
	v_mfma_f32_16x16x32_bf16 v[78:81], v[152:155], v[208:211], v[78:81]
	v_mfma_f32_16x16x32_bf16 v[74:77], v[160:163], v[208:211], v[74:77]
	s_setprio 0
	s_setprio 1
	v_mfma_f32_16x16x32_bf16 v[118:121], v[164:167], v[180:183], v[118:121]
	v_mfma_f32_16x16x32_bf16 v[114:117], v[172:175], v[180:183], v[114:117]
	v_mfma_f32_16x16x32_bf16 v[102:105], v[164:167], v[188:191], v[102:105]
	v_mfma_f32_16x16x32_bf16 v[98:101], v[172:175], v[188:191], v[98:101]
	v_mfma_f32_16x16x32_bf16 v[86:89], v[164:167], v[196:199], v[86:89]
	v_mfma_f32_16x16x32_bf16 v[82:85], v[172:175], v[196:199], v[82:85]
	v_mfma_f32_16x16x32_bf16 v[70:73], v[164:167], v[204:207], v[70:73]
	v_mfma_f32_16x16x32_bf16 v[66:69], v[172:175], v[204:207], v[66:69]
	v_mfma_f32_16x16x32_bf16 v[118:121], v[168:171], v[184:187], v[118:121]
	v_mfma_f32_16x16x32_bf16 v[114:117], v[176:179], v[184:187], v[114:117]
	v_mfma_f32_16x16x32_bf16 v[102:105], v[168:171], v[192:195], v[102:105]
	v_mfma_f32_16x16x32_bf16 v[98:101], v[176:179], v[192:195], v[98:101]
	v_mfma_f32_16x16x32_bf16 v[86:89], v[168:171], v[200:203], v[86:89]
	v_mfma_f32_16x16x32_bf16 v[82:85], v[176:179], v[200:203], v[82:85]
	v_mfma_f32_16x16x32_bf16 v[70:73], v[168:171], v[208:211], v[70:73]
	v_mfma_f32_16x16x32_bf16 v[66:69], v[176:179], v[208:211], v[66:69]
	s_setprio 0
	s_barrier
	s_add_i32 s20, s20, s31
	v_lshl_add_u64 v[144:145], v[144:145], 0, s[82:83]
	s_mov_b32 m0, s20
	ds_read_b128 v[180:183], v147 offset:49152
	ds_read_b128 v[184:187], v147 offset:50176
	ds_read_b128 v[188:191], v147 offset:51200
	ds_read_b128 v[192:195], v147 offset:52224
	ds_read_b128 v[196:199], v147 offset:53248
	ds_read_b128 v[200:203], v147 offset:54272
	ds_read_b128 v[204:207], v147 offset:55296
	ds_read_b128 v[208:211], v147 offset:56320
	global_load_lds_dwordx4 v[144:145], off
	s_add_i32 m0, s20, 0x2000
	s_add_u32 s20, s26, 0x40080
	v_lshl_add_u64 v[144:145], v[212:213], 0, s[82:83]
	s_addc_u32 s21, s27, 0
	s_add_i32 s23, s23, s31
	global_load_lds_dwordx4 v[144:145], off
	v_lshl_add_u64 v[144:145], s[20:21], 0, v[0:1]
	s_mov_b32 m0, s23
	s_nop 0
	global_load_lds_dwordx4 v[144:145], off
	v_lshl_add_u64 v[144:145], s[20:21], 0, v[130:131]
	s_add_i32 m0, s23, 0x2000
	s_nop 0
	global_load_lds_dwordx4 v[144:145], off
	v_lshl_add_u64 v[144:145], v[214:215], 0, s[82:83]
	s_mov_b32 m0, s40
	s_nop 0
	global_load_lds_dwordx4 v[144:145], off
	v_lshl_add_u64 v[144:145], v[216:217], 0, s[82:83]
	s_mov_b32 m0, s41
	s_nop 0
	global_load_lds_dwordx4 v[144:145], off
	s_waitcnt vmcnt(8)
	s_waitcnt lgkmcnt(0)
	s_barrier
	s_setprio 1
	s_waitcnt lgkmcnt(0)
	v_mfma_f32_16x16x32_bf16 v[62:65], v[148:151], v[180:183], v[62:65]
	v_mfma_f32_16x16x32_bf16 v[58:61], v[156:159], v[180:183], v[58:61]
	v_mfma_f32_16x16x32_bf16 v[46:49], v[148:151], v[188:191], v[46:49]
	v_mfma_f32_16x16x32_bf16 v[42:45], v[156:159], v[188:191], v[42:45]
	v_mfma_f32_16x16x32_bf16 v[22:25], v[148:151], v[196:199], v[22:25]
	v_mfma_f32_16x16x32_bf16 v[18:21], v[156:159], v[196:199], v[18:21]
	v_mfma_f32_16x16x32_bf16 v[6:9], v[148:151], v[204:207], v[6:9]
	v_mfma_f32_16x16x32_bf16 v[2:5], v[156:159], v[204:207], v[2:5]
	v_mfma_f32_16x16x32_bf16 v[62:65], v[152:155], v[184:187], v[62:65]
	v_mfma_f32_16x16x32_bf16 v[58:61], v[160:163], v[184:187], v[58:61]
	v_mfma_f32_16x16x32_bf16 v[46:49], v[152:155], v[192:195], v[46:49]
	v_mfma_f32_16x16x32_bf16 v[42:45], v[160:163], v[192:195], v[42:45]
	v_mfma_f32_16x16x32_bf16 v[22:25], v[152:155], v[200:203], v[22:25]
	v_mfma_f32_16x16x32_bf16 v[18:21], v[160:163], v[200:203], v[18:21]
	v_mfma_f32_16x16x32_bf16 v[6:9], v[152:155], v[208:211], v[6:9]
	v_mfma_f32_16x16x32_bf16 v[2:5], v[160:163], v[208:211], v[2:5]
	s_setprio 0
	s_setprio 1
	v_mfma_f32_16x16x32_bf16 v[54:57], v[164:167], v[180:183], v[54:57]
	v_mfma_f32_16x16x32_bf16 v[50:53], v[172:175], v[180:183], v[50:53]
	v_mfma_f32_16x16x32_bf16 v[38:41], v[164:167], v[188:191], v[38:41]
	v_mfma_f32_16x16x32_bf16 v[34:37], v[172:175], v[188:191], v[34:37]
	v_mfma_f32_16x16x32_bf16 v[26:29], v[164:167], v[196:199], v[26:29]
	v_mfma_f32_16x16x32_bf16 v[30:33], v[172:175], v[196:199], v[30:33]
	v_mfma_f32_16x16x32_bf16 v[10:13], v[164:167], v[204:207], v[10:13]
	v_mfma_f32_16x16x32_bf16 v[14:17], v[172:175], v[204:207], v[14:17]
	v_mfma_f32_16x16x32_bf16 v[54:57], v[168:171], v[184:187], v[54:57]
	v_mfma_f32_16x16x32_bf16 v[50:53], v[176:179], v[184:187], v[50:53]
	v_mfma_f32_16x16x32_bf16 v[38:41], v[168:171], v[192:195], v[38:41]
	v_mfma_f32_16x16x32_bf16 v[34:37], v[176:179], v[192:195], v[34:37]
	v_mfma_f32_16x16x32_bf16 v[26:29], v[168:171], v[200:203], v[26:29]
	v_mfma_f32_16x16x32_bf16 v[30:33], v[176:179], v[200:203], v[30:33]
	v_mfma_f32_16x16x32_bf16 v[10:13], v[168:171], v[208:211], v[10:13]
	v_mfma_f32_16x16x32_bf16 v[14:17], v[176:179], v[208:211], v[14:17]
	s_setprio 0
	s_barrier
	s_branch .Lpeel_latch_264

.Lpeel_latch_264:
	s_add_i32 s48, s48, 2
	s_add_u32 s46, s46, 0x100
	s_addc_u32 s47, s47, 0
	s_cmp_gt_u32 s48, 13
	s_mov_b64 s[20:21], s[24:25]
	s_cbranch_scc0 .LBB0_264
	s_and_b64 vcc, exec, s[10:11]
	s_cbranch_vccz .LBB0_267
	s_barrier

.Luq_two_trips:
	s_add_u32 s68, s26, s36
	s_addc_u32 s69, s27, 0
	s_add_u32 s23, s68, 0x100
	s_addc_u32 s37, s69, 0
	s_and_b64 s[34:35], s[30:31], exec
	s_cselect_b32 s34, s13, s23
	s_cselect_b32 s35, s9, s37
	s_add_u32 s23, s24, s36
	s_addc_u32 s36, s25, 0
	s_add_u32 s23, s23, 0x100
	s_addc_u32 s36, s36, 0
	s_and_b64 s[30:31], s[30:31], exec
	s_cselect_b32 s37, s15, s36
	s_cselect_b32 s36, s53, s23
	s_add_i32 s23, 0, 0x10000
	s_add_i32 s31, 0, 0x14000
	s_add_i32 s65, s23, s40
	v_add_u32_e32 v154, s23, v140
	v_add_u32_e32 v170, s31, v140
	s_add_i32 m0, s41, 0xc000
	s_add_i32 s56, s41, 0xe000
	s_add_i32 s60, s65, 0x2000
	ds_read_b128 v[142:145], v154
	ds_read_b128 v[146:149], v154 offset:1024
	ds_read_b128 v[150:153], v154 offset:2048
	ds_read_b128 v[154:157], v154 offset:3072
	ds_read_b128 v[158:161], v170
	ds_read_b128 v[162:165], v170 offset:1024
	ds_read_b128 v[166:169], v170 offset:2048
	ds_read_b128 v[170:173], v170 offset:3072
	s_add_u32 s38, s36, 0x10000
	s_addc_u32 s39, s37, 0
	s_add_i32 s59, 0, 0x18000
	s_add_i32 s64, s31, s40
	s_add_i32 s55, s59, s40
	s_add_i32 s61, s64, 0x2000
	s_add_i32 s57, 0, 0x1c000
	s_add_i32 s54, s55, 0x2000
	s_add_u32 s30, s36, 0x10080
	s_addc_u32 s31, s37, 0
	s_add_i32 s67, s57, s40
	s_add_i32 s66, s67, 0x2000
	v_lshl_add_u64 v[206:207], s[68:69], 0, v[136:137]
	v_lshl_add_u64 v[206:207], v[206:207], 0, s[82:83]
	ds_read_b128 v[174:177], v141
	ds_read_b128 v[178:181], v141 offset:1024
	ds_read_b128 v[182:185], v141 offset:2048
	ds_read_b128 v[186:189], v141 offset:3072
	ds_read_b128 v[190:193], v141 offset:4096
	ds_read_b128 v[194:197], v141 offset:5120
	ds_read_b128 v[198:201], v141 offset:6144
	ds_read_b128 v[202:205], v141 offset:7168
	global_load_lds_dwordx4 v[206:207], off
	v_lshl_add_u64 v[206:207], s[68:69], 0, v[138:139]
	v_lshl_add_u64 v[206:207], v[206:207], 0, s[82:83]
	s_mov_b32 m0, s56
	s_nop 0
	global_load_lds_dwordx4 v[206:207], off
	s_waitcnt vmcnt(8)
	s_waitcnt lgkmcnt(0)
	s_barrier
	s_setprio 1
	s_waitcnt lgkmcnt(0)
	v_mfma_f32_16x16x32_bf16 v[126:129], v[142:145], v[174:177], 0
	v_mfma_f32_16x16x32_bf16 v[122:125], v[150:153], v[174:177], 0
	v_mfma_f32_16x16x32_bf16 v[118:121], v[142:145], v[182:185], 0
	v_mfma_f32_16x16x32_bf16 v[110:113], v[150:153], v[182:185], 0
	v_mfma_f32_16x16x32_bf16 v[102:105], v[142:145], v[190:193], 0
	v_mfma_f32_16x16x32_bf16 v[94:97], v[150:153], v[190:193], 0
	v_mfma_f32_16x16x32_bf16 v[86:89], v[142:145], v[198:201], 0
	v_mfma_f32_16x16x32_bf16 v[78:81], v[150:153], v[198:201], 0
	v_mfma_f32_16x16x32_bf16 v[126:129], v[146:149], v[178:181], v[126:129]
	v_mfma_f32_16x16x32_bf16 v[122:125], v[154:157], v[178:181], v[122:125]
	v_mfma_f32_16x16x32_bf16 v[118:121], v[146:149], v[186:189], v[118:121]
	v_mfma_f32_16x16x32_bf16 v[110:113], v[154:157], v[186:189], v[110:113]
	v_mfma_f32_16x16x32_bf16 v[102:105], v[146:149], v[194:197], v[102:105]
	v_mfma_f32_16x16x32_bf16 v[94:97], v[154:157], v[194:197], v[94:97]
	v_mfma_f32_16x16x32_bf16 v[86:89], v[146:149], v[202:205], v[86:89]
	v_mfma_f32_16x16x32_bf16 v[78:81], v[154:157], v[202:205], v[78:81]
	s_setprio 0
	s_setprio 1
	v_mfma_f32_16x16x32_bf16 v[114:117], v[158:161], v[174:177], 0
	v_mfma_f32_16x16x32_bf16 v[106:109], v[166:169], v[174:177], 0
	v_mfma_f32_16x16x32_bf16 v[98:101], v[158:161], v[182:185], 0
	v_mfma_f32_16x16x32_bf16 v[90:93], v[166:169], v[182:185], 0
	v_mfma_f32_16x16x32_bf16 v[82:85], v[158:161], v[190:193], 0
	v_mfma_f32_16x16x32_bf16 v[74:77], v[166:169], v[190:193], 0
	v_mfma_f32_16x16x32_bf16 v[70:73], v[158:161], v[198:201], 0
	v_mfma_f32_16x16x32_bf16 v[66:69], v[166:169], v[198:201], 0
	v_mfma_f32_16x16x32_bf16 v[114:117], v[162:165], v[178:181], v[114:117]
	v_mfma_f32_16x16x32_bf16 v[106:109], v[170:173], v[178:181], v[106:109]
	v_mfma_f32_16x16x32_bf16 v[98:101], v[162:165], v[186:189], v[98:101]
	v_mfma_f32_16x16x32_bf16 v[90:93], v[170:173], v[186:189], v[90:93]
	v_mfma_f32_16x16x32_bf16 v[82:85], v[162:165], v[194:197], v[82:85]
	v_mfma_f32_16x16x32_bf16 v[74:77], v[170:173], v[194:197], v[74:77]
	v_mfma_f32_16x16x32_bf16 v[70:73], v[162:165], v[202:205], v[70:73]
	v_mfma_f32_16x16x32_bf16 v[66:69], v[170:173], v[202:205], v[66:69]
	s_setprio 0
	s_barrier
	s_mov_b32 m0, s65
	v_lshl_add_u64 v[206:207], s[36:37], 0, v[0:1]
	ds_read_b128 v[174:177], v141 offset:16384
	ds_read_b128 v[178:181], v141 offset:17408
	ds_read_b128 v[182:185], v141 offset:18432
	ds_read_b128 v[186:189], v141 offset:19456
	ds_read_b128 v[190:193], v141 offset:20480
	ds_read_b128 v[194:197], v141 offset:21504
	ds_read_b128 v[198:201], v141 offset:22528
	ds_read_b128 v[202:205], v141 offset:23552
	global_load_lds_dwordx4 v[206:207], off
	v_lshl_add_u64 v[208:209], s[36:37], 0, v[130:131]
	s_mov_b32 m0, s60
	v_lshl_add_u64 v[210:211], s[38:39], 0, v[0:1]
	global_load_lds_dwordx4 v[208:209], off
	s_mov_b32 m0, s64
	v_lshl_add_u64 v[212:213], s[34:35], 0, v[134:135]
	global_load_lds_dwordx4 v[210:211], off
	v_lshl_add_u64 v[210:211], s[38:39], 0, v[130:131]
	s_mov_b32 m0, s61
	s_nop 0
	global_load_lds_dwordx4 v[210:211], off
	v_lshl_add_u64 v[210:211], s[34:35], 0, v[132:133]
	s_mov_b32 m0, s41
	s_nop 0
	global_load_lds_dwordx4 v[210:211], off
	s_mov_b32 m0, s11
	s_nop 0
	global_load_lds_dwordx4 v[212:213], off
	s_waitcnt vmcnt(8)
	s_waitcnt lgkmcnt(0)
	s_barrier
	s_setprio 1
	s_waitcnt lgkmcnt(0)
	v_mfma_f32_16x16x32_bf16 v[62:65], v[142:145], v[174:177], 0
	v_mfma_f32_16x16x32_bf16 v[58:61], v[150:153], v[174:177], 0
	v_mfma_f32_16x16x32_bf16 v[46:49], v[142:145], v[182:185], 0
	v_mfma_f32_16x16x32_bf16 v[38:41], v[150:153], v[182:185], 0
	v_mfma_f32_16x16x32_bf16 v[22:25], v[142:145], v[190:193], 0
	v_mfma_f32_16x16x32_bf16 v[14:17], v[150:153], v[190:193], 0
	v_mfma_f32_16x16x32_bf16 v[6:9], v[142:145], v[198:201], 0
	v_mfma_f32_16x16x32_bf16 v[2:5], v[150:153], v[198:201], 0
	v_mfma_f32_16x16x32_bf16 v[62:65], v[146:149], v[178:181], v[62:65]
	v_mfma_f32_16x16x32_bf16 v[58:61], v[154:157], v[178:181], v[58:61]
	v_mfma_f32_16x16x32_bf16 v[46:49], v[146:149], v[186:189], v[46:49]
	v_mfma_f32_16x16x32_bf16 v[38:41], v[154:157], v[186:189], v[38:41]
	v_mfma_f32_16x16x32_bf16 v[22:25], v[146:149], v[194:197], v[22:25]
	v_mfma_f32_16x16x32_bf16 v[14:17], v[154:157], v[194:197], v[14:17]
	v_mfma_f32_16x16x32_bf16 v[6:9], v[146:149], v[202:205], v[6:9]
	v_mfma_f32_16x16x32_bf16 v[2:5], v[154:157], v[202:205], v[2:5]
	s_setprio 0
	s_setprio 1
	v_mfma_f32_16x16x32_bf16 v[42:45], v[158:161], v[174:177], 0
	v_mfma_f32_16x16x32_bf16 v[34:37], v[166:169], v[174:177], 0
	v_mfma_f32_16x16x32_bf16 v[18:21], v[158:161], v[182:185], 0
	v_mfma_f32_16x16x32_bf16 v[10:13], v[166:169], v[182:185], 0
	v_mfma_f32_16x16x32_bf16 v[54:57], v[158:161], v[190:193], 0
	v_mfma_f32_16x16x32_bf16 v[50:53], v[166:169], v[190:193], 0
	v_mfma_f32_16x16x32_bf16 v[30:33], v[158:161], v[198:201], 0
	v_mfma_f32_16x16x32_bf16 v[26:29], v[166:169], v[198:201], 0
	v_mfma_f32_16x16x32_bf16 v[42:45], v[162:165], v[178:181], v[42:45]
	v_mfma_f32_16x16x32_bf16 v[34:37], v[170:173], v[178:181], v[34:37]
	v_mfma_f32_16x16x32_bf16 v[18:21], v[162:165], v[186:189], v[18:21]
	v_mfma_f32_16x16x32_bf16 v[10:13], v[170:173], v[186:189], v[10:13]
	v_mfma_f32_16x16x32_bf16 v[54:57], v[162:165], v[194:197], v[54:57]
	v_mfma_f32_16x16x32_bf16 v[50:53], v[170:173], v[194:197], v[50:53]
	v_mfma_f32_16x16x32_bf16 v[30:33], v[162:165], v[202:205], v[30:33]
	v_mfma_f32_16x16x32_bf16 v[26:29], v[170:173], v[202:205], v[26:29]
	s_setprio 0
	s_barrier
	v_add_u32_e32 v154, s59, v140
	v_add_u32_e32 v170, s57, v140
	ds_read_b128 v[142:145], v154
	ds_read_b128 v[146:149], v154 offset:1024
	ds_read_b128 v[150:153], v154 offset:2048
	ds_read_b128 v[154:157], v154 offset:3072
	ds_read_b128 v[158:161], v170
	ds_read_b128 v[162:165], v170 offset:1024
	ds_read_b128 v[166:169], v170 offset:2048
	ds_read_b128 v[170:173], v170 offset:3072
	s_mov_b32 m0, s42
	v_lshl_add_u64 v[214:215], s[34:35], 0, v[136:137]
	ds_read_b128 v[174:177], v141 offset:32768
	ds_read_b128 v[178:181], v141 offset:33792
	ds_read_b128 v[182:185], v141 offset:34816
	ds_read_b128 v[186:189], v141 offset:35840
	ds_read_b128 v[190:193], v141 offset:36864
	ds_read_b128 v[194:197], v141 offset:37888
	ds_read_b128 v[198:201], v141 offset:38912
	ds_read_b128 v[202:205], v141 offset:39936
	global_load_lds_dwordx4 v[214:215], off
	v_lshl_add_u64 v[214:215], s[34:35], 0, v[138:139]
	s_mov_b32 m0, s43
	s_nop 0
	global_load_lds_dwordx4 v[214:215], off
	s_waitcnt vmcnt(8)
	s_waitcnt lgkmcnt(0)
	s_barrier
	s_setprio 1
	s_waitcnt lgkmcnt(0)
	v_mfma_f32_16x16x32_bf16 v[126:129], v[142:145], v[174:177], v[126:129]
	v_mfma_f32_16x16x32_bf16 v[122:125], v[150:153], v[174:177], v[122:125]
	v_mfma_f32_16x16x32_bf16 v[118:121], v[142:145], v[182:185], v[118:121]
	v_mfma_f32_16x16x32_bf16 v[110:113], v[150:153], v[182:185], v[110:113]
	v_mfma_f32_16x16x32_bf16 v[102:105], v[142:145], v[190:193], v[102:105]
	v_mfma_f32_16x16x32_bf16 v[94:97], v[150:153], v[190:193], v[94:97]
	v_mfma_f32_16x16x32_bf16 v[86:89], v[142:145], v[198:201], v[86:89]
	v_mfma_f32_16x16x32_bf16 v[78:81], v[150:153], v[198:201], v[78:81]
	v_mfma_f32_16x16x32_bf16 v[126:129], v[146:149], v[178:181], v[126:129]
	v_mfma_f32_16x16x32_bf16 v[122:125], v[154:157], v[178:181], v[122:125]
	v_mfma_f32_16x16x32_bf16 v[118:121], v[146:149], v[186:189], v[118:121]
	v_mfma_f32_16x16x32_bf16 v[110:113], v[154:157], v[186:189], v[110:113]
	v_mfma_f32_16x16x32_bf16 v[102:105], v[146:149], v[194:197], v[102:105]
	v_mfma_f32_16x16x32_bf16 v[94:97], v[154:157], v[194:197], v[94:97]
	v_mfma_f32_16x16x32_bf16 v[86:89], v[146:149], v[202:205], v[86:89]
	v_mfma_f32_16x16x32_bf16 v[78:81], v[154:157], v[202:205], v[78:81]
	s_setprio 0
	s_setprio 1
	v_mfma_f32_16x16x32_bf16 v[114:117], v[158:161], v[174:177], v[114:117]
	v_mfma_f32_16x16x32_bf16 v[106:109], v[166:169], v[174:177], v[106:109]
	v_mfma_f32_16x16x32_bf16 v[98:101], v[158:161], v[182:185], v[98:101]
	v_mfma_f32_16x16x32_bf16 v[90:93], v[166:169], v[182:185], v[90:93]
	v_mfma_f32_16x16x32_bf16 v[82:85], v[158:161], v[190:193], v[82:85]
	v_mfma_f32_16x16x32_bf16 v[74:77], v[166:169], v[190:193], v[74:77]
	v_mfma_f32_16x16x32_bf16 v[70:73], v[158:161], v[198:201], v[70:73]
	v_mfma_f32_16x16x32_bf16 v[66:69], v[166:169], v[198:201], v[66:69]
	v_mfma_f32_16x16x32_bf16 v[114:117], v[162:165], v[178:181], v[114:117]
	v_mfma_f32_16x16x32_bf16 v[106:109], v[170:173], v[178:181], v[106:109]
	v_mfma_f32_16x16x32_bf16 v[98:101], v[162:165], v[186:189], v[98:101]
	v_mfma_f32_16x16x32_bf16 v[90:93], v[170:173], v[186:189], v[90:93]
	v_mfma_f32_16x16x32_bf16 v[82:85], v[162:165], v[194:197], v[82:85]
	v_mfma_f32_16x16x32_bf16 v[74:77], v[170:173], v[194:197], v[74:77]
	v_mfma_f32_16x16x32_bf16 v[70:73], v[162:165], v[202:205], v[70:73]
	v_mfma_f32_16x16x32_bf16 v[66:69], v[170:173], v[202:205], v[66:69]
	s_setprio 0
	s_barrier
	s_mov_b32 m0, s55
	v_lshl_add_u64 v[206:207], v[206:207], 0, s[82:83]
	ds_read_b128 v[174:177], v141 offset:49152
	ds_read_b128 v[178:181], v141 offset:50176
	ds_read_b128 v[182:185], v141 offset:51200
	ds_read_b128 v[186:189], v141 offset:52224
	ds_read_b128 v[190:193], v141 offset:53248
	ds_read_b128 v[194:197], v141 offset:54272
	ds_read_b128 v[198:201], v141 offset:55296
	ds_read_b128 v[202:205], v141 offset:56320
	global_load_lds_dwordx4 v[206:207], off
	v_lshl_add_u64 v[206:207], v[208:209], 0, s[82:83]
	s_mov_b32 m0, s54
	s_nop 0
	global_load_lds_dwordx4 v[206:207], off
	v_lshl_add_u64 v[206:207], s[30:31], 0, v[0:1]
	s_mov_b32 m0, s67
	s_nop 0
	global_load_lds_dwordx4 v[206:207], off
	v_lshl_add_u64 v[206:207], s[30:31], 0, v[130:131]
	s_mov_b32 m0, s66
	s_nop 0
	global_load_lds_dwordx4 v[206:207], off
	v_lshl_add_u64 v[206:207], v[210:211], 0, s[82:83]
	s_mov_b32 m0, s46
	s_nop 0
	global_load_lds_dwordx4 v[206:207], off
	v_lshl_add_u64 v[206:207], v[212:213], 0, s[82:83]
	s_mov_b32 m0, s47
	s_nop 0
	global_load_lds_dwordx4 v[206:207], off
	s_waitcnt vmcnt(8)
	s_waitcnt lgkmcnt(0)
	s_barrier
	s_setprio 1
	s_waitcnt lgkmcnt(0)
	v_mfma_f32_16x16x32_bf16 v[62:65], v[142:145], v[174:177], v[62:65]
	v_mfma_f32_16x16x32_bf16 v[58:61], v[150:153], v[174:177], v[58:61]
	v_mfma_f32_16x16x32_bf16 v[46:49], v[142:145], v[182:185], v[46:49]
	v_mfma_f32_16x16x32_bf16 v[38:41], v[150:153], v[182:185], v[38:41]
	v_mfma_f32_16x16x32_bf16 v[22:25], v[142:145], v[190:193], v[22:25]
	v_mfma_f32_16x16x32_bf16 v[14:17], v[150:153], v[190:193], v[14:17]
	v_mfma_f32_16x16x32_bf16 v[6:9], v[142:145], v[198:201], v[6:9]
	v_mfma_f32_16x16x32_bf16 v[2:5], v[150:153], v[198:201], v[2:5]
	v_mfma_f32_16x16x32_bf16 v[62:65], v[146:149], v[178:181], v[62:65]
	v_mfma_f32_16x16x32_bf16 v[58:61], v[154:157], v[178:181], v[58:61]
	v_mfma_f32_16x16x32_bf16 v[46:49], v[146:149], v[186:189], v[46:49]
	v_mfma_f32_16x16x32_bf16 v[38:41], v[154:157], v[186:189], v[38:41]
	v_mfma_f32_16x16x32_bf16 v[22:25], v[146:149], v[194:197], v[22:25]
	v_mfma_f32_16x16x32_bf16 v[14:17], v[154:157], v[194:197], v[14:17]
	v_mfma_f32_16x16x32_bf16 v[6:9], v[146:149], v[202:205], v[6:9]
	v_mfma_f32_16x16x32_bf16 v[2:5], v[154:157], v[202:205], v[2:5]
	s_setprio 0
	s_setprio 1
	v_mfma_f32_16x16x32_bf16 v[42:45], v[158:161], v[174:177], v[42:45]
	v_mfma_f32_16x16x32_bf16 v[34:37], v[166:169], v[174:177], v[34:37]
	v_mfma_f32_16x16x32_bf16 v[18:21], v[158:161], v[182:185], v[18:21]
	v_mfma_f32_16x16x32_bf16 v[10:13], v[166:169], v[182:185], v[10:13]
	v_mfma_f32_16x16x32_bf16 v[54:57], v[158:161], v[190:193], v[54:57]
	v_mfma_f32_16x16x32_bf16 v[50:53], v[166:169], v[190:193], v[50:53]
	v_mfma_f32_16x16x32_bf16 v[30:33], v[158:161], v[198:201], v[30:33]
	v_mfma_f32_16x16x32_bf16 v[26:29], v[166:169], v[198:201], v[26:29]
	v_mfma_f32_16x16x32_bf16 v[42:45], v[162:165], v[178:181], v[42:45]
	v_mfma_f32_16x16x32_bf16 v[34:37], v[170:173], v[178:181], v[34:37]
	v_mfma_f32_16x16x32_bf16 v[18:21], v[162:165], v[186:189], v[18:21]
	v_mfma_f32_16x16x32_bf16 v[10:13], v[170:173], v[186:189], v[10:13]
	v_mfma_f32_16x16x32_bf16 v[54:57], v[162:165], v[194:197], v[54:57]
	v_mfma_f32_16x16x32_bf16 v[50:53], v[170:173], v[194:197], v[50:53]
	v_mfma_f32_16x16x32_bf16 v[30:33], v[162:165], v[202:205], v[30:33]
	v_mfma_f32_16x16x32_bf16 v[26:29], v[170:173], v[202:205], v[26:29]
	s_setprio 0
	s_barrier
	s_branch .Lpeel_latch_514

.Lpeel_latch_514:
	s_movk_i32 s36, 0x100
	s_andn2_b64 vcc, exec, s[28:29]
	s_mov_b64 s[30:31], -1
	s_mov_b64 s[28:29], 0
	s_cbranch_vccz .LBB0_514
	s_and_b64 vcc, exec, s[6:7]
	s_cbranch_vccz .LBB0_517
	s_barrier

.LBB0_1218:
	s_lshl_b32 s16, s55, 8
	s_ashr_i32 s17, s16, 31
	s_lshl_b64 s[16:17], s[16:17], 11
	s_add_u32 s16, s34, s16
	s_addc_u32 s17, s35, s17
	s_and_b64 s[20:21], s[18:19], exec
	s_cselect_b32 s60, s17, s25
	s_cselect_b32 s61, s16, s24
	s_ashr_i32 s15, s14, 31
	s_lshl_b64 s[20:21], s[14:15], 19
	s_add_u32 s20, s36, s20
	s_addc_u32 s21, s37, s21
	s_and_b64 s[28:29], s[18:19], exec
	s_cselect_b32 s15, s21, s27
	s_cselect_b32 s64, s20, s26
	s_add_u32 s65, s26, 0x100
	v_mov_b32_e32 v10, 0
	s_addc_u32 s66, s27, 0
	s_mov_b32 s67, -2
	s_add_u32 s26, s24, 0x100
	s_addc_u32 s27, s25, 0
	s_cmp_eq_u32 s67, 12
	s_cselect_b32 s31, s60, s27
	s_cselect_b32 s30, s61, s26
	s_cselect_b32 s29, s15, s66
	s_cselect_b32 s28, s64, s65
	s_add_i32 s23, 0, 0x10000
	v_add_u32_e32 v144, s23, v146
	s_add_i32 s56, 0, 0x14000
	ds_read_b128 v[148:151], v144
	ds_read_b128 v[152:155], v144 offset:1024
	ds_read_b128 v[156:159], v144 offset:2048
	ds_read_b128 v[160:163], v144 offset:3072
	v_add_u32_e32 v144, s56, v146
	ds_read_b128 v[164:167], v144
	ds_read_b128 v[168:171], v144 offset:1024
	ds_read_b128 v[172:175], v144 offset:2048
	ds_read_b128 v[176:179], v144 offset:3072
	v_lshl_add_u64 v[144:145], s[24:25], 0, v[142:143]
	s_add_i32 m0, s47, 0xc000
	ds_read_b128 v[180:183], v147
	ds_read_b128 v[184:187], v147 offset:1024
	ds_read_b128 v[188:191], v147 offset:2048
	ds_read_b128 v[192:195], v147 offset:3072
	ds_read_b128 v[196:199], v147 offset:4096
	ds_read_b128 v[200:203], v147 offset:5120
	ds_read_b128 v[204:207], v147 offset:6144
	ds_read_b128 v[208:211], v147 offset:7168
	global_load_lds_dwordx4 v[144:145], off
	v_lshl_add_u64 v[144:145], s[24:25], 0, v[140:141]
	s_add_i32 m0, s47, 0xe000
	s_nop 0
	global_load_lds_dwordx4 v[144:145], off
	s_waitcnt vmcnt(8)
	s_waitcnt lgkmcnt(0)
	s_barrier
	s_setprio 1
	s_waitcnt lgkmcnt(0)
	v_mfma_f32_16x16x32_bf16 v[126:129], v[148:151], v[180:183], 0
	v_mfma_f32_16x16x32_bf16 v[122:125], v[156:159], v[180:183], 0
	v_mfma_f32_16x16x32_bf16 v[118:121], v[148:151], v[188:191], 0
	v_mfma_f32_16x16x32_bf16 v[110:113], v[156:159], v[188:191], 0
	v_mfma_f32_16x16x32_bf16 v[102:105], v[148:151], v[196:199], 0
	v_mfma_f32_16x16x32_bf16 v[94:97], v[156:159], v[196:199], 0
	v_mfma_f32_16x16x32_bf16 v[86:89], v[148:151], v[204:207], 0
	v_mfma_f32_16x16x32_bf16 v[78:81], v[156:159], v[204:207], 0
	v_mfma_f32_16x16x32_bf16 v[126:129], v[152:155], v[184:187], v[126:129]
	v_mfma_f32_16x16x32_bf16 v[122:125], v[160:163], v[184:187], v[122:125]
	v_mfma_f32_16x16x32_bf16 v[118:121], v[152:155], v[192:195], v[118:121]
	v_mfma_f32_16x16x32_bf16 v[110:113], v[160:163], v[192:195], v[110:113]
	v_mfma_f32_16x16x32_bf16 v[102:105], v[152:155], v[200:203], v[102:105]
	v_mfma_f32_16x16x32_bf16 v[94:97], v[160:163], v[200:203], v[94:97]
	v_mfma_f32_16x16x32_bf16 v[86:89], v[152:155], v[208:211], v[86:89]
	v_mfma_f32_16x16x32_bf16 v[78:81], v[160:163], v[208:211], v[78:81]
	s_setprio 0
	s_setprio 1
	v_mfma_f32_16x16x32_bf16 v[114:117], v[164:167], v[180:183], 0
	v_mfma_f32_16x16x32_bf16 v[106:109], v[172:175], v[180:183], 0
	v_mfma_f32_16x16x32_bf16 v[98:101], v[164:167], v[188:191], 0
	v_mfma_f32_16x16x32_bf16 v[90:93], v[172:175], v[188:191], 0
	v_mfma_f32_16x16x32_bf16 v[82:85], v[164:167], v[196:199], 0
	v_mfma_f32_16x16x32_bf16 v[74:77], v[172:175], v[196:199], 0
	v_mfma_f32_16x16x32_bf16 v[70:73], v[164:167], v[204:207], 0
	v_mfma_f32_16x16x32_bf16 v[66:69], v[172:175], v[204:207], 0
	v_mfma_f32_16x16x32_bf16 v[114:117], v[168:171], v[184:187], v[114:117]
	v_mfma_f32_16x16x32_bf16 v[106:109], v[176:179], v[184:187], v[106:109]
	v_mfma_f32_16x16x32_bf16 v[98:101], v[168:171], v[192:195], v[98:101]
	v_mfma_f32_16x16x32_bf16 v[90:93], v[176:179], v[192:195], v[90:93]
	v_mfma_f32_16x16x32_bf16 v[82:85], v[168:171], v[200:203], v[82:85]
	v_mfma_f32_16x16x32_bf16 v[74:77], v[176:179], v[200:203], v[74:77]
	v_mfma_f32_16x16x32_bf16 v[70:73], v[168:171], v[208:211], v[70:73]
	v_mfma_f32_16x16x32_bf16 v[66:69], v[176:179], v[208:211], v[66:69]
	s_setprio 0
	s_barrier
	s_add_i32 s23, s23, s3
	v_lshl_add_u64 v[144:145], s[28:29], 0, v[0:1]
	s_mov_b32 m0, s23
	ds_read_b128 v[180:183], v147 offset:16384
	ds_read_b128 v[184:187], v147 offset:17408
	ds_read_b128 v[188:191], v147 offset:18432
	ds_read_b128 v[192:195], v147 offset:19456
	ds_read_b128 v[196:199], v147 offset:20480
	ds_read_b128 v[200:203], v147 offset:21504
	ds_read_b128 v[204:207], v147 offset:22528
	ds_read_b128 v[208:211], v147 offset:23552
	global_load_lds_dwordx4 v[144:145], off
	s_add_i32 m0, s23, 0x2000
	s_add_u32 s24, s28, 0x40000
	v_lshl_add_u64 v[212:213], s[28:29], 0, v[130:131]
	s_addc_u32 s25, s29, 0
	s_add_i32 s23, s56, s3
	global_load_lds_dwordx4 v[212:213], off
	v_lshl_add_u64 v[214:215], s[24:25], 0, v[0:1]
	s_mov_b32 m0, s23
	v_lshl_add_u64 v[216:217], s[30:31], 0, v[134:135]
	global_load_lds_dwordx4 v[214:215], off
	v_lshl_add_u64 v[214:215], s[24:25], 0, v[130:131]
	s_add_i32 m0, s23, 0x2000
	s_nop 0
	global_load_lds_dwordx4 v[214:215], off
	v_lshl_add_u64 v[214:215], s[30:31], 0, v[132:133]
	s_mov_b32 m0, s47
	s_nop 0
	global_load_lds_dwordx4 v[214:215], off
	s_mov_b32 m0, s48
	s_nop 0
	global_load_lds_dwordx4 v[216:217], off
	s_waitcnt vmcnt(8)
	s_waitcnt lgkmcnt(0)
	s_barrier
	s_setprio 1
	s_waitcnt lgkmcnt(0)
	v_mfma_f32_16x16x32_bf16 v[62:65], v[148:151], v[180:183], 0
	v_mfma_f32_16x16x32_bf16 v[58:61], v[156:159], v[180:183], 0
	v_mfma_f32_16x16x32_bf16 v[46:49], v[148:151], v[188:191], 0
	v_mfma_f32_16x16x32_bf16 v[38:41], v[156:159], v[188:191], 0
	v_mfma_f32_16x16x32_bf16 v[22:25], v[148:151], v[196:199], 0
	v_mfma_f32_16x16x32_bf16 v[14:17], v[156:159], v[196:199], 0
	v_mfma_f32_16x16x32_bf16 v[6:9], v[148:151], v[204:207], 0
	v_mfma_f32_16x16x32_bf16 v[2:5], v[156:159], v[204:207], 0
	v_mfma_f32_16x16x32_bf16 v[62:65], v[152:155], v[184:187], v[62:65]
	v_mfma_f32_16x16x32_bf16 v[58:61], v[160:163], v[184:187], v[58:61]
	v_mfma_f32_16x16x32_bf16 v[46:49], v[152:155], v[192:195], v[46:49]
	v_mfma_f32_16x16x32_bf16 v[38:41], v[160:163], v[192:195], v[38:41]
	v_mfma_f32_16x16x32_bf16 v[22:25], v[152:155], v[200:203], v[22:25]
	v_mfma_f32_16x16x32_bf16 v[14:17], v[160:163], v[200:203], v[14:17]
	v_mfma_f32_16x16x32_bf16 v[6:9], v[152:155], v[208:211], v[6:9]
	v_mfma_f32_16x16x32_bf16 v[2:5], v[160:163], v[208:211], v[2:5]
	s_setprio 0
	s_setprio 1
	v_mfma_f32_16x16x32_bf16 v[42:45], v[164:167], v[180:183], 0
	v_mfma_f32_16x16x32_bf16 v[34:37], v[172:175], v[180:183], 0
	v_mfma_f32_16x16x32_bf16 v[18:21], v[164:167], v[188:191], 0
	v_mfma_f32_16x16x32_bf16 v[10:13], v[172:175], v[188:191], 0
	v_mfma_f32_16x16x32_bf16 v[54:57], v[164:167], v[196:199], 0
	v_mfma_f32_16x16x32_bf16 v[50:53], v[172:175], v[196:199], 0
	v_mfma_f32_16x16x32_bf16 v[30:33], v[164:167], v[204:207], 0
	v_mfma_f32_16x16x32_bf16 v[26:29], v[172:175], v[204:207], 0
	v_mfma_f32_16x16x32_bf16 v[42:45], v[168:171], v[184:187], v[42:45]
	v_mfma_f32_16x16x32_bf16 v[34:37], v[176:179], v[184:187], v[34:37]
	v_mfma_f32_16x16x32_bf16 v[18:21], v[168:171], v[192:195], v[18:21]
	v_mfma_f32_16x16x32_bf16 v[10:13], v[176:179], v[192:195], v[10:13]
	v_mfma_f32_16x16x32_bf16 v[54:57], v[168:171], v[200:203], v[54:57]
	v_mfma_f32_16x16x32_bf16 v[50:53], v[176:179], v[200:203], v[50:53]
	v_mfma_f32_16x16x32_bf16 v[30:33], v[168:171], v[208:211], v[30:33]
	v_mfma_f32_16x16x32_bf16 v[26:29], v[176:179], v[208:211], v[26:29]
	s_setprio 0
	s_barrier
	s_add_i32 s23, 0, 0x18000
	s_add_i32 s56, 0, 0x1c000
	v_add_u32_e32 v160, s23, v146
	v_add_u32_e32 v176, s56, v146
	ds_read_b128 v[148:151], v160
	ds_read_b128 v[152:155], v160 offset:1024
	ds_read_b128 v[156:159], v160 offset:2048
	ds_read_b128 v[160:163], v160 offset:3072
	ds_read_b128 v[164:167], v176
	ds_read_b128 v[168:171], v176 offset:1024
	ds_read_b128 v[172:175], v176 offset:2048
	ds_read_b128 v[176:179], v176 offset:3072
	s_mov_b32 m0, s49
	v_lshl_add_u64 v[218:219], s[30:31], 0, v[136:137]
	ds_read_b128 v[180:183], v147 offset:32768
	ds_read_b128 v[184:187], v147 offset:33792
	ds_read_b128 v[188:191], v147 offset:34816
	ds_read_b128 v[192:195], v147 offset:35840
	ds_read_b128 v[196:199], v147 offset:36864
	ds_read_b128 v[200:203], v147 offset:37888
	ds_read_b128 v[204:207], v147 offset:38912
	ds_read_b128 v[208:211], v147 offset:39936
	global_load_lds_dwordx4 v[218:219], off
	v_lshl_add_u64 v[218:219], s[30:31], 0, v[138:139]
	s_mov_b32 m0, s50
	s_nop 0
	global_load_lds_dwordx4 v[218:219], off
	s_waitcnt vmcnt(8)
	s_waitcnt lgkmcnt(0)
	s_barrier
	s_setprio 1
	s_waitcnt lgkmcnt(0)
	v_mfma_f32_16x16x32_bf16 v[126:129], v[148:151], v[180:183], v[126:129]
	v_mfma_f32_16x16x32_bf16 v[122:125], v[156:159], v[180:183], v[122:125]
	v_mfma_f32_16x16x32_bf16 v[118:121], v[148:151], v[188:191], v[118:121]
	v_mfma_f32_16x16x32_bf16 v[110:113], v[156:159], v[188:191], v[110:113]
	v_mfma_f32_16x16x32_bf16 v[102:105], v[148:151], v[196:199], v[102:105]
	v_mfma_f32_16x16x32_bf16 v[94:97], v[156:159], v[196:199], v[94:97]
	v_mfma_f32_16x16x32_bf16 v[86:89], v[148:151], v[204:207], v[86:89]
	v_mfma_f32_16x16x32_bf16 v[78:81], v[156:159], v[204:207], v[78:81]
	v_mfma_f32_16x16x32_bf16 v[126:129], v[152:155], v[184:187], v[126:129]
	v_mfma_f32_16x16x32_bf16 v[122:125], v[160:163], v[184:187], v[122:125]
	v_mfma_f32_16x16x32_bf16 v[118:121], v[152:155], v[192:195], v[118:121]
	v_mfma_f32_16x16x32_bf16 v[110:113], v[160:163], v[192:195], v[110:113]
	v_mfma_f32_16x16x32_bf16 v[102:105], v[152:155], v[200:203], v[102:105]
	v_mfma_f32_16x16x32_bf16 v[94:97], v[160:163], v[200:203], v[94:97]
	v_mfma_f32_16x16x32_bf16 v[86:89], v[152:155], v[208:211], v[86:89]
	v_mfma_f32_16x16x32_bf16 v[78:81], v[160:163], v[208:211], v[78:81]
	s_setprio 0
	s_setprio 1
	v_mfma_f32_16x16x32_bf16 v[114:117], v[164:167], v[180:183], v[114:117]
	v_mfma_f32_16x16x32_bf16 v[106:109], v[172:175], v[180:183], v[106:109]
	v_mfma_f32_16x16x32_bf16 v[98:101], v[164:167], v[188:191], v[98:101]
	v_mfma_f32_16x16x32_bf16 v[90:93], v[172:175], v[188:191], v[90:93]
	v_mfma_f32_16x16x32_bf16 v[82:85], v[164:167], v[196:199], v[82:85]
	v_mfma_f32_16x16x32_bf16 v[74:77], v[172:175], v[196:199], v[74:77]
	v_mfma_f32_16x16x32_bf16 v[70:73], v[164:167], v[204:207], v[70:73]
	v_mfma_f32_16x16x32_bf16 v[66:69], v[172:175], v[204:207], v[66:69]
	v_mfma_f32_16x16x32_bf16 v[114:117], v[168:171], v[184:187], v[114:117]
	v_mfma_f32_16x16x32_bf16 v[106:109], v[176:179], v[184:187], v[106:109]
	v_mfma_f32_16x16x32_bf16 v[98:101], v[168:171], v[192:195], v[98:101]
	v_mfma_f32_16x16x32_bf16 v[90:93], v[176:179], v[192:195], v[90:93]
	v_mfma_f32_16x16x32_bf16 v[82:85], v[168:171], v[200:203], v[82:85]
	v_mfma_f32_16x16x32_bf16 v[74:77], v[176:179], v[200:203], v[74:77]
	v_mfma_f32_16x16x32_bf16 v[70:73], v[168:171], v[208:211], v[70:73]
	v_mfma_f32_16x16x32_bf16 v[66:69], v[176:179], v[208:211], v[66:69]
	s_setprio 0
	s_barrier
	s_add_i32 s23, s23, s3
	v_lshl_add_u64 v[144:145], v[144:145], 0, s[82:83]
	s_mov_b32 m0, s23
	ds_read_b128 v[180:183], v147 offset:49152
	ds_read_b128 v[184:187], v147 offset:50176
	ds_read_b128 v[188:191], v147 offset:51200
	ds_read_b128 v[192:195], v147 offset:52224
	ds_read_b128 v[196:199], v147 offset:53248
	ds_read_b128 v[200:203], v147 offset:54272
	ds_read_b128 v[204:207], v147 offset:55296
	ds_read_b128 v[208:211], v147 offset:56320
	global_load_lds_dwordx4 v[144:145], off
	s_add_i32 m0, s23, 0x2000
	s_add_u32 s24, s28, 0x40080
	v_lshl_add_u64 v[144:145], v[212:213], 0, s[82:83]
	s_addc_u32 s25, s29, 0
	s_add_i32 s23, s56, s3
	global_load_lds_dwordx4 v[144:145], off
	v_lshl_add_u64 v[144:145], s[24:25], 0, v[0:1]
	s_mov_b32 m0, s23
	s_nop 0
	global_load_lds_dwordx4 v[144:145], off
	v_lshl_add_u64 v[144:145], s[24:25], 0, v[130:131]
	s_add_i32 m0, s23, 0x2000
	s_nop 0
	global_load_lds_dwordx4 v[144:145], off
	v_lshl_add_u64 v[144:145], v[214:215], 0, s[82:83]
	s_mov_b32 m0, s51
	s_nop 0
	global_load_lds_dwordx4 v[144:145], off
	v_lshl_add_u64 v[144:145], v[216:217], 0, s[82:83]
	s_mov_b32 m0, s52
	s_nop 0
	global_load_lds_dwordx4 v[144:145], off
	s_waitcnt vmcnt(8)
	s_waitcnt lgkmcnt(0)
	s_barrier
	s_setprio 1
	s_waitcnt lgkmcnt(0)
	v_mfma_f32_16x16x32_bf16 v[62:65], v[148:151], v[180:183], v[62:65]
	v_mfma_f32_16x16x32_bf16 v[58:61], v[156:159], v[180:183], v[58:61]
	v_mfma_f32_16x16x32_bf16 v[46:49], v[148:151], v[188:191], v[46:49]
	v_mfma_f32_16x16x32_bf16 v[38:41], v[156:159], v[188:191], v[38:41]
	v_mfma_f32_16x16x32_bf16 v[22:25], v[148:151], v[196:199], v[22:25]
	v_mfma_f32_16x16x32_bf16 v[14:17], v[156:159], v[196:199], v[14:17]
	v_mfma_f32_16x16x32_bf16 v[6:9], v[148:151], v[204:207], v[6:9]
	v_mfma_f32_16x16x32_bf16 v[2:5], v[156:159], v[204:207], v[2:5]
	v_mfma_f32_16x16x32_bf16 v[62:65], v[152:155], v[184:187], v[62:65]
	v_mfma_f32_16x16x32_bf16 v[58:61], v[160:163], v[184:187], v[58:61]
	v_mfma_f32_16x16x32_bf16 v[46:49], v[152:155], v[192:195], v[46:49]
	v_mfma_f32_16x16x32_bf16 v[38:41], v[160:163], v[192:195], v[38:41]
	v_mfma_f32_16x16x32_bf16 v[22:25], v[152:155], v[200:203], v[22:25]
	v_mfma_f32_16x16x32_bf16 v[14:17], v[160:163], v[200:203], v[14:17]
	v_mfma_f32_16x16x32_bf16 v[6:9], v[152:155], v[208:211], v[6:9]
	v_mfma_f32_16x16x32_bf16 v[2:5], v[160:163], v[208:211], v[2:5]
	s_setprio 0
	s_setprio 1
	v_mfma_f32_16x16x32_bf16 v[42:45], v[164:167], v[180:183], v[42:45]
	v_mfma_f32_16x16x32_bf16 v[34:37], v[172:175], v[180:183], v[34:37]
	v_mfma_f32_16x16x32_bf16 v[18:21], v[164:167], v[188:191], v[18:21]
	v_mfma_f32_16x16x32_bf16 v[10:13], v[172:175], v[188:191], v[10:13]
	v_mfma_f32_16x16x32_bf16 v[54:57], v[164:167], v[196:199], v[54:57]
	v_mfma_f32_16x16x32_bf16 v[50:53], v[172:175], v[196:199], v[50:53]
	v_mfma_f32_16x16x32_bf16 v[30:33], v[164:167], v[204:207], v[30:33]
	v_mfma_f32_16x16x32_bf16 v[26:29], v[172:175], v[204:207], v[26:29]
	v_mfma_f32_16x16x32_bf16 v[42:45], v[168:171], v[184:187], v[42:45]
	v_mfma_f32_16x16x32_bf16 v[34:37], v[176:179], v[184:187], v[34:37]
	v_mfma_f32_16x16x32_bf16 v[18:21], v[168:171], v[192:195], v[18:21]
	v_mfma_f32_16x16x32_bf16 v[10:13], v[176:179], v[192:195], v[10:13]
	v_mfma_f32_16x16x32_bf16 v[54:57], v[168:171], v[200:203], v[54:57]
	v_mfma_f32_16x16x32_bf16 v[50:53], v[176:179], v[200:203], v[50:53]
	v_mfma_f32_16x16x32_bf16 v[30:33], v[168:171], v[208:211], v[30:33]
	v_mfma_f32_16x16x32_bf16 v[26:29], v[176:179], v[208:211], v[26:29]
	s_setprio 0
	s_barrier
	s_branch .Lpeel_latch_1219

.Lpeel_latch_1219:
	s_add_i32 s67, s67, 2
	s_add_u32 s65, s65, 0x100
	s_addc_u32 s66, s66, 0
	s_cmp_gt_u32 s67, 13
	s_mov_b64 s[24:25], s[26:27]
	s_cbranch_scc0 .LBB0_1219
	s_and_b64 vcc, exec, s[12:13]
	s_cbranch_vccz .LBB0_1222
	s_barrier

.LBB0_1475:
	v_mov_b32_e32 v139, v1
	v_mov_b32_e32 v141, v1
	s_add_u32 s21, s26, 0x100
	v_mov_b32_e32 v2, 0
	s_addc_u32 s49, s27, 0
	v_lshl_add_u64 v[142:143], s[16:17], 0, v[140:141]
	v_lshl_add_u64 v[144:145], s[16:17], 0, v[138:139]
	s_mov_b32 s50, -2
	s_mov_b64 s[26:27], 0
	s_add_u32 s28, s26, 0x100
	s_addc_u32 s29, s27, 0
	s_add_u32 s23, s21, s26
	s_addc_u32 s34, s49, s27
	s_cmpk_eq_i32 s26, 0x700
	s_cselect_b64 vcc, -1, 0
	s_and_b64 s[30:31], vcc, exec
	s_cselect_b32 s51, 0, s28
	s_cselect_b32 s35, 0, s29
	s_cselect_b32 s30, s8, s23
	s_cselect_b32 s31, s9, s34
	s_add_u32 s34, s10, s51
	s_addc_u32 s35, s11, s35
	s_add_i32 s23, 0, 0x10000
	v_add_u32_e32 v141, s23, v150
	s_add_i32 s51, 0, 0x14000
	ds_read_b128 v[156:159], v141
	ds_read_b128 v[160:163], v141 offset:1024
	ds_read_b128 v[164:167], v141 offset:2048
	ds_read_b128 v[168:171], v141 offset:3072
	v_add_u32_e32 v141, s51, v150
	ds_read_b128 v[172:175], v141
	ds_read_b128 v[176:179], v141 offset:1024
	ds_read_b128 v[180:183], v141 offset:2048
	ds_read_b128 v[184:187], v141 offset:3072
	v_cndmask_b32_e32 v0, v134, v154, vcc
	v_cndmask_b32_e32 v220, v136, v153, vcc
	v_cndmask_b32_e32 v135, v138, v152, vcc
	v_cndmask_b32_e32 v139, v140, v151, vcc
	v_lshl_add_u64 v[222:223], v[144:145], 0, s[26:27]
	s_add_i32 m0, s38, 0xc000
	ds_read_b128 v[188:191], v137
	ds_read_b128 v[192:195], v137 offset:1024
	ds_read_b128 v[196:199], v137 offset:2048
	ds_read_b128 v[200:203], v137 offset:3072
	ds_read_b128 v[204:207], v137 offset:4096
	ds_read_b128 v[208:211], v137 offset:5120
	ds_read_b128 v[212:215], v137 offset:6144
	ds_read_b128 v[216:219], v137 offset:7168
	global_load_lds_dwordx4 v[222:223], off
	v_lshl_add_u64 v[222:223], v[142:143], 0, s[26:27]
	s_add_i32 m0, s38, 0xe000
	s_nop 0
	global_load_lds_dwordx4 v[222:223], off
	s_waitcnt vmcnt(8)
	s_waitcnt lgkmcnt(0)
	s_barrier
	s_setprio 1
	s_waitcnt lgkmcnt(0)
	v_mfma_f32_16x16x32_bf16 v[126:129], v[156:159], v[188:191], 0
	v_mfma_f32_16x16x32_bf16 v[118:121], v[164:167], v[188:191], 0
	v_mfma_f32_16x16x32_bf16 v[110:113], v[156:159], v[196:199], 0
	v_mfma_f32_16x16x32_bf16 v[102:105], v[164:167], v[196:199], 0
	v_mfma_f32_16x16x32_bf16 v[94:97], v[156:159], v[204:207], 0
	v_mfma_f32_16x16x32_bf16 v[86:89], v[164:167], v[204:207], 0
	v_mfma_f32_16x16x32_bf16 v[78:81], v[156:159], v[212:215], 0
	v_mfma_f32_16x16x32_bf16 v[70:73], v[164:167], v[212:215], 0
	v_mfma_f32_16x16x32_bf16 v[126:129], v[160:163], v[192:195], v[126:129]
	v_mfma_f32_16x16x32_bf16 v[118:121], v[168:171], v[192:195], v[118:121]
	v_mfma_f32_16x16x32_bf16 v[110:113], v[160:163], v[200:203], v[110:113]
	v_mfma_f32_16x16x32_bf16 v[102:105], v[168:171], v[200:203], v[102:105]
	v_mfma_f32_16x16x32_bf16 v[94:97], v[160:163], v[208:211], v[94:97]
	v_mfma_f32_16x16x32_bf16 v[86:89], v[168:171], v[208:211], v[86:89]
	v_mfma_f32_16x16x32_bf16 v[78:81], v[160:163], v[216:219], v[78:81]
	v_mfma_f32_16x16x32_bf16 v[70:73], v[168:171], v[216:219], v[70:73]
	s_setprio 0
	s_setprio 1
	v_mfma_f32_16x16x32_bf16 v[122:125], v[172:175], v[188:191], 0
	v_mfma_f32_16x16x32_bf16 v[114:117], v[180:183], v[188:191], 0
	v_mfma_f32_16x16x32_bf16 v[106:109], v[172:175], v[196:199], 0
	v_mfma_f32_16x16x32_bf16 v[98:101], v[180:183], v[196:199], 0
	v_mfma_f32_16x16x32_bf16 v[90:93], v[172:175], v[204:207], 0
	v_mfma_f32_16x16x32_bf16 v[82:85], v[180:183], v[204:207], 0
	v_mfma_f32_16x16x32_bf16 v[74:77], v[172:175], v[212:215], 0
	v_mfma_f32_16x16x32_bf16 v[66:69], v[180:183], v[212:215], 0
	v_mfma_f32_16x16x32_bf16 v[122:125], v[176:179], v[192:195], v[122:125]
	v_mfma_f32_16x16x32_bf16 v[114:117], v[184:187], v[192:195], v[114:117]
	v_mfma_f32_16x16x32_bf16 v[106:109], v[176:179], v[200:203], v[106:109]
	v_mfma_f32_16x16x32_bf16 v[98:101], v[184:187], v[200:203], v[98:101]
	v_mfma_f32_16x16x32_bf16 v[90:93], v[176:179], v[208:211], v[90:93]
	v_mfma_f32_16x16x32_bf16 v[82:85], v[184:187], v[208:211], v[82:85]
	v_mfma_f32_16x16x32_bf16 v[74:77], v[176:179], v[216:219], v[74:77]
	v_mfma_f32_16x16x32_bf16 v[66:69], v[184:187], v[216:219], v[66:69]
	s_setprio 0
	s_barrier
	s_add_i32 s23, s23, s37
	v_lshl_add_u64 v[222:223], s[30:31], 0, v[130:131]
	s_mov_b32 m0, s23
	ds_read_b128 v[188:191], v137 offset:16384
	ds_read_b128 v[192:195], v137 offset:17408
	ds_read_b128 v[196:199], v137 offset:18432
	ds_read_b128 v[200:203], v137 offset:19456
	ds_read_b128 v[204:207], v137 offset:20480
	ds_read_b128 v[208:211], v137 offset:21504
	ds_read_b128 v[212:215], v137 offset:22528
	ds_read_b128 v[216:219], v137 offset:23552
	global_load_lds_dwordx4 v[222:223], off
	s_add_i32 m0, s23, 0x2000
	s_add_u32 s26, s30, 0x40000
	v_lshl_add_u64 v[224:225], s[30:31], 0, v[132:133]
	s_addc_u32 s27, s31, 0
	s_add_i32 s23, s51, s37
	global_load_lds_dwordx4 v[224:225], off
	v_lshl_add_u64 v[226:227], s[26:27], 0, v[130:131]
	s_mov_b32 m0, s23
	v_mov_b32_e32 v221, v1
	global_load_lds_dwordx4 v[226:227], off
	v_lshl_add_u64 v[226:227], s[26:27], 0, v[132:133]
	s_add_i32 m0, s23, 0x2000
	s_nop 0
	global_load_lds_dwordx4 v[226:227], off
	s_mov_b32 m0, s38
	v_lshl_add_u64 v[226:227], s[34:35], 0, v[0:1]
	global_load_lds_dwordx4 v0, s[34:35]
	s_mov_b32 m0, s39
	s_nop 0
	global_load_lds_dwordx4 v220, s[34:35]
	s_waitcnt vmcnt(8)
	s_waitcnt lgkmcnt(0)
	v_lshl_add_u64 v[220:221], s[34:35], 0, v[220:221]
	s_barrier
	s_setprio 1
	s_waitcnt lgkmcnt(0)
	v_mfma_f32_16x16x32_bf16 v[62:65], v[156:159], v[188:191], 0
	v_mfma_f32_16x16x32_bf16 v[54:57], v[164:167], v[188:191], 0
	v_mfma_f32_16x16x32_bf16 v[46:49], v[156:159], v[196:199], 0
	v_mfma_f32_16x16x32_bf16 v[38:41], v[164:167], v[196:199], 0
	v_mfma_f32_16x16x32_bf16 v[30:33], v[156:159], v[204:207], 0
	v_mfma_f32_16x16x32_bf16 v[22:25], v[164:167], v[204:207], 0
	v_mfma_f32_16x16x32_bf16 v[14:17], v[156:159], v[212:215], 0
	v_mfma_f32_16x16x32_bf16 v[6:9], v[164:167], v[212:215], 0
	v_mfma_f32_16x16x32_bf16 v[62:65], v[160:163], v[192:195], v[62:65]
	v_mfma_f32_16x16x32_bf16 v[54:57], v[168:171], v[192:195], v[54:57]
	v_mfma_f32_16x16x32_bf16 v[46:49], v[160:163], v[200:203], v[46:49]
	v_mfma_f32_16x16x32_bf16 v[38:41], v[168:171], v[200:203], v[38:41]
	v_mfma_f32_16x16x32_bf16 v[30:33], v[160:163], v[208:211], v[30:33]
	v_mfma_f32_16x16x32_bf16 v[22:25], v[168:171], v[208:211], v[22:25]
	v_mfma_f32_16x16x32_bf16 v[14:17], v[160:163], v[216:219], v[14:17]
	v_mfma_f32_16x16x32_bf16 v[6:9], v[168:171], v[216:219], v[6:9]
	s_setprio 0
	s_setprio 1
	v_mfma_f32_16x16x32_bf16 v[58:61], v[172:175], v[188:191], 0
	v_mfma_f32_16x16x32_bf16 v[50:53], v[180:183], v[188:191], 0
	v_mfma_f32_16x16x32_bf16 v[42:45], v[172:175], v[196:199], 0
	v_mfma_f32_16x16x32_bf16 v[34:37], v[180:183], v[196:199], 0
	v_mfma_f32_16x16x32_bf16 v[26:29], v[172:175], v[204:207], 0
	v_mfma_f32_16x16x32_bf16 v[18:21], v[180:183], v[204:207], 0
	v_mfma_f32_16x16x32_bf16 v[10:13], v[172:175], v[212:215], 0
	v_mfma_f32_16x16x32_bf16 v[2:5], v[180:183], v[212:215], 0
	v_mfma_f32_16x16x32_bf16 v[58:61], v[176:179], v[192:195], v[58:61]
	v_mfma_f32_16x16x32_bf16 v[50:53], v[184:187], v[192:195], v[50:53]
	v_mfma_f32_16x16x32_bf16 v[42:45], v[176:179], v[200:203], v[42:45]
	v_mfma_f32_16x16x32_bf16 v[34:37], v[184:187], v[200:203], v[34:37]
	v_mfma_f32_16x16x32_bf16 v[26:29], v[176:179], v[208:211], v[26:29]
	v_mfma_f32_16x16x32_bf16 v[18:21], v[184:187], v[208:211], v[18:21]
	v_mfma_f32_16x16x32_bf16 v[10:13], v[176:179], v[216:219], v[10:13]
	v_mfma_f32_16x16x32_bf16 v[2:5], v[184:187], v[216:219], v[2:5]
	s_setprio 0
	s_barrier
	s_add_i32 s23, 0, 0x18000
	v_add_u32_e32 v0, s23, v150
	s_add_i32 s51, 0, 0x1c000
	ds_read_b128 v[156:159], v0
	ds_read_b128 v[160:163], v0 offset:1024
	ds_read_b128 v[164:167], v0 offset:2048
	ds_read_b128 v[168:171], v0 offset:3072
	v_add_u32_e32 v0, s51, v150
	ds_read_b128 v[172:175], v0
	ds_read_b128 v[176:179], v0 offset:1024
	ds_read_b128 v[180:183], v0 offset:2048
	ds_read_b128 v[184:187], v0 offset:3072
	s_mov_b32 m0, s40
	ds_read_b128 v[188:191], v137 offset:32768
	ds_read_b128 v[192:195], v137 offset:33792
	ds_read_b128 v[196:199], v137 offset:34816
	ds_read_b128 v[200:203], v137 offset:35840
	ds_read_b128 v[204:207], v137 offset:36864
	ds_read_b128 v[208:211], v137 offset:37888
	ds_read_b128 v[212:215], v137 offset:38912
	ds_read_b128 v[216:219], v137 offset:39936
	global_load_lds_dwordx4 v135, s[34:35]
	s_mov_b32 m0, s41
	s_nop 0
	global_load_lds_dwordx4 v139, s[34:35]
	s_waitcnt vmcnt(8)
	s_waitcnt lgkmcnt(0)
	s_barrier
	s_setprio 1
	s_waitcnt lgkmcnt(0)
	v_mfma_f32_16x16x32_bf16 v[126:129], v[156:159], v[188:191], v[126:129]
	v_mfma_f32_16x16x32_bf16 v[118:121], v[164:167], v[188:191], v[118:121]
	v_mfma_f32_16x16x32_bf16 v[110:113], v[156:159], v[196:199], v[110:113]
	v_mfma_f32_16x16x32_bf16 v[102:105], v[164:167], v[196:199], v[102:105]
	v_mfma_f32_16x16x32_bf16 v[94:97], v[156:159], v[204:207], v[94:97]
	v_mfma_f32_16x16x32_bf16 v[86:89], v[164:167], v[204:207], v[86:89]
	v_mfma_f32_16x16x32_bf16 v[78:81], v[156:159], v[212:215], v[78:81]
	v_mfma_f32_16x16x32_bf16 v[70:73], v[164:167], v[212:215], v[70:73]
	v_mfma_f32_16x16x32_bf16 v[126:129], v[160:163], v[192:195], v[126:129]
	v_mfma_f32_16x16x32_bf16 v[118:121], v[168:171], v[192:195], v[118:121]
	v_mfma_f32_16x16x32_bf16 v[110:113], v[160:163], v[200:203], v[110:113]
	v_mfma_f32_16x16x32_bf16 v[102:105], v[168:171], v[200:203], v[102:105]
	v_mfma_f32_16x16x32_bf16 v[94:97], v[160:163], v[208:211], v[94:97]
	v_mfma_f32_16x16x32_bf16 v[86:89], v[168:171], v[208:211], v[86:89]
	v_mfma_f32_16x16x32_bf16 v[78:81], v[160:163], v[216:219], v[78:81]
	v_mfma_f32_16x16x32_bf16 v[70:73], v[168:171], v[216:219], v[70:73]
	s_setprio 0
	s_setprio 1
	v_mfma_f32_16x16x32_bf16 v[122:125], v[172:175], v[188:191], v[122:125]
	v_mfma_f32_16x16x32_bf16 v[114:117], v[180:183], v[188:191], v[114:117]
	v_mfma_f32_16x16x32_bf16 v[106:109], v[172:175], v[196:199], v[106:109]
	v_mfma_f32_16x16x32_bf16 v[98:101], v[180:183], v[196:199], v[98:101]
	v_mfma_f32_16x16x32_bf16 v[90:93], v[172:175], v[204:207], v[90:93]
	v_mfma_f32_16x16x32_bf16 v[82:85], v[180:183], v[204:207], v[82:85]
	v_mfma_f32_16x16x32_bf16 v[74:77], v[172:175], v[212:215], v[74:77]
	v_mfma_f32_16x16x32_bf16 v[66:69], v[180:183], v[212:215], v[66:69]
	v_mfma_f32_16x16x32_bf16 v[122:125], v[176:179], v[192:195], v[122:125]
	v_mfma_f32_16x16x32_bf16 v[114:117], v[184:187], v[192:195], v[114:117]
	v_mfma_f32_16x16x32_bf16 v[106:109], v[176:179], v[200:203], v[106:109]
	v_mfma_f32_16x16x32_bf16 v[98:101], v[184:187], v[200:203], v[98:101]
	v_mfma_f32_16x16x32_bf16 v[90:93], v[176:179], v[208:211], v[90:93]
	v_mfma_f32_16x16x32_bf16 v[82:85], v[184:187], v[208:211], v[82:85]
	v_mfma_f32_16x16x32_bf16 v[74:77], v[176:179], v[216:219], v[74:77]
	v_mfma_f32_16x16x32_bf16 v[66:69], v[184:187], v[216:219], v[66:69]
	s_setprio 0
	s_barrier
	s_add_i32 s23, s23, s37
	v_lshl_add_u64 v[222:223], v[222:223], 0, s[82:83]
	s_mov_b32 m0, s23
	ds_read_b128 v[188:191], v137 offset:49152
	ds_read_b128 v[192:195], v137 offset:50176
	ds_read_b128 v[196:199], v137 offset:51200
	ds_read_b128 v[200:203], v137 offset:52224
	ds_read_b128 v[204:207], v137 offset:53248
	ds_read_b128 v[208:211], v137 offset:54272
	ds_read_b128 v[212:215], v137 offset:55296
	ds_read_b128 v[216:219], v137 offset:56320
	global_load_lds_dwordx4 v[222:223], off
	s_add_i32 m0, s23, 0x2000
	s_add_u32 s26, s30, 0x40080
	v_lshl_add_u64 v[222:223], v[224:225], 0, s[82:83]
	s_addc_u32 s27, s31, 0
	s_add_i32 s23, s51, s37
	global_load_lds_dwordx4 v[222:223], off
	v_lshl_add_u64 v[222:223], s[26:27], 0, v[130:131]
	s_mov_b32 m0, s23
	v_lshl_add_u64 v[220:221], v[220:221], 0, s[82:83]
	global_load_lds_dwordx4 v[222:223], off
	v_lshl_add_u64 v[222:223], s[26:27], 0, v[132:133]
	s_add_i32 m0, s23, 0x2000
	s_nop 0
	global_load_lds_dwordx4 v[222:223], off
	v_lshl_add_u64 v[222:223], v[226:227], 0, s[82:83]
	s_mov_b32 m0, s43
	s_nop 0
	global_load_lds_dwordx4 v[222:223], off
	s_mov_b32 m0, s44
	s_nop 0
	global_load_lds_dwordx4 v[220:221], off
	s_waitcnt vmcnt(8)
	s_waitcnt lgkmcnt(0)
	s_barrier
	s_setprio 1
	s_waitcnt lgkmcnt(0)
	v_mfma_f32_16x16x32_bf16 v[62:65], v[156:159], v[188:191], v[62:65]
	v_mfma_f32_16x16x32_bf16 v[54:57], v[164:167], v[188:191], v[54:57]
	v_mfma_f32_16x16x32_bf16 v[46:49], v[156:159], v[196:199], v[46:49]
	v_mfma_f32_16x16x32_bf16 v[38:41], v[164:167], v[196:199], v[38:41]
	v_mfma_f32_16x16x32_bf16 v[30:33], v[156:159], v[204:207], v[30:33]
	v_mfma_f32_16x16x32_bf16 v[22:25], v[164:167], v[204:207], v[22:25]
	v_mfma_f32_16x16x32_bf16 v[14:17], v[156:159], v[212:215], v[14:17]
	v_mfma_f32_16x16x32_bf16 v[6:9], v[164:167], v[212:215], v[6:9]
	v_mfma_f32_16x16x32_bf16 v[62:65], v[160:163], v[192:195], v[62:65]
	v_mfma_f32_16x16x32_bf16 v[54:57], v[168:171], v[192:195], v[54:57]
	v_mfma_f32_16x16x32_bf16 v[46:49], v[160:163], v[200:203], v[46:49]
	v_mfma_f32_16x16x32_bf16 v[38:41], v[168:171], v[200:203], v[38:41]
	v_mfma_f32_16x16x32_bf16 v[30:33], v[160:163], v[208:211], v[30:33]
	v_mfma_f32_16x16x32_bf16 v[22:25], v[168:171], v[208:211], v[22:25]
	v_mfma_f32_16x16x32_bf16 v[14:17], v[160:163], v[216:219], v[14:17]
	v_mfma_f32_16x16x32_bf16 v[6:9], v[168:171], v[216:219], v[6:9]
	s_setprio 0
	s_setprio 1
	v_mfma_f32_16x16x32_bf16 v[58:61], v[172:175], v[188:191], v[58:61]
	v_mfma_f32_16x16x32_bf16 v[50:53], v[180:183], v[188:191], v[50:53]
	v_mfma_f32_16x16x32_bf16 v[42:45], v[172:175], v[196:199], v[42:45]
	v_mfma_f32_16x16x32_bf16 v[34:37], v[180:183], v[196:199], v[34:37]
	v_mfma_f32_16x16x32_bf16 v[26:29], v[172:175], v[204:207], v[26:29]
	v_mfma_f32_16x16x32_bf16 v[18:21], v[180:183], v[204:207], v[18:21]
	v_mfma_f32_16x16x32_bf16 v[10:13], v[172:175], v[212:215], v[10:13]
	v_mfma_f32_16x16x32_bf16 v[2:5], v[180:183], v[212:215], v[2:5]
	v_mfma_f32_16x16x32_bf16 v[58:61], v[176:179], v[192:195], v[58:61]
	v_mfma_f32_16x16x32_bf16 v[50:53], v[184:187], v[192:195], v[50:53]
	v_mfma_f32_16x16x32_bf16 v[42:45], v[176:179], v[200:203], v[42:45]
	v_mfma_f32_16x16x32_bf16 v[34:37], v[184:187], v[200:203], v[34:37]
	v_mfma_f32_16x16x32_bf16 v[26:29], v[176:179], v[208:211], v[26:29]
	v_mfma_f32_16x16x32_bf16 v[18:21], v[184:187], v[208:211], v[18:21]
	v_mfma_f32_16x16x32_bf16 v[10:13], v[176:179], v[216:219], v[10:13]
	v_mfma_f32_16x16x32_bf16 v[2:5], v[184:187], v[216:219], v[2:5]
	s_setprio 0
	s_barrier
	s_branch .Lpeel_latch_1476

.Lpeel_latch_1476:
	s_add_i32 s50, s50, 2
	s_cmp_gt_u32 s50, 13
	s_mov_b64 s[26:27], s[28:29]
	s_cbranch_scc0 .LBB0_1476
	s_and_b64 vcc, exec, s[18:19]
	s_cbranch_vccz .LBB0_1479
	s_barrier

.LBB0_1551:
	s_lshl_b32 s26, s64, 8
	s_ashr_i32 s27, s26, 31
	s_lshl_b64 s[26:27], s[26:27], 11
	s_add_u32 s26, s38, s26
	s_addc_u32 s27, s39, s27
	s_and_b64 s[34:35], s[34:35], exec
	s_cselect_b32 s21, s27, s29
	s_cselect_b32 s66, s26, s28
	s_add_u32 s67, s30, 0x100
	v_mov_b32_e32 v10, 0
	s_addc_u32 s68, s31, 0
	s_mov_b32 s69, -2
	s_add_u32 s30, s28, 0x100
	s_addc_u32 s31, s29, 0
	s_cmp_eq_u32 s69, 12
	s_cselect_b32 s37, s21, s31
	s_cselect_b32 s36, s66, s30
	s_cselect_b32 s35, s25, s68
	s_cselect_b32 s34, s24, s67
	s_add_i32 s23, 0, 0x10000
	v_add_u32_e32 v144, s23, v146
	s_add_i32 s56, 0, 0x14000
	ds_read_b128 v[148:151], v144
	ds_read_b128 v[152:155], v144 offset:1024
	ds_read_b128 v[156:159], v144 offset:2048
	ds_read_b128 v[160:163], v144 offset:3072
	v_add_u32_e32 v144, s56, v146
	ds_read_b128 v[164:167], v144
	ds_read_b128 v[168:171], v144 offset:1024
	ds_read_b128 v[172:175], v144 offset:2048
	ds_read_b128 v[176:179], v144 offset:3072
	v_lshl_add_u64 v[144:145], s[28:29], 0, v[142:143]
	s_add_i32 m0, s51, 0xc000
	ds_read_b128 v[180:183], v147
	ds_read_b128 v[184:187], v147 offset:1024
	ds_read_b128 v[188:191], v147 offset:2048
	ds_read_b128 v[192:195], v147 offset:3072
	ds_read_b128 v[196:199], v147 offset:4096
	ds_read_b128 v[200:203], v147 offset:5120
	ds_read_b128 v[204:207], v147 offset:6144
	ds_read_b128 v[208:211], v147 offset:7168
	global_load_lds_dwordx4 v[144:145], off
	v_lshl_add_u64 v[144:145], s[28:29], 0, v[140:141]
	s_add_i32 m0, s51, 0xe000
	s_nop 0
	global_load_lds_dwordx4 v[144:145], off
	s_waitcnt vmcnt(8)
	s_waitcnt lgkmcnt(0)
	s_barrier
	s_setprio 1
	s_waitcnt lgkmcnt(0)
	v_mfma_f32_16x16x32_bf16 v[126:129], v[148:151], v[180:183], 0
	v_mfma_f32_16x16x32_bf16 v[122:125], v[156:159], v[180:183], 0
	v_mfma_f32_16x16x32_bf16 v[118:121], v[148:151], v[188:191], 0
	v_mfma_f32_16x16x32_bf16 v[110:113], v[156:159], v[188:191], 0
	v_mfma_f32_16x16x32_bf16 v[102:105], v[148:151], v[196:199], 0
	v_mfma_f32_16x16x32_bf16 v[94:97], v[156:159], v[196:199], 0
	v_mfma_f32_16x16x32_bf16 v[86:89], v[148:151], v[204:207], 0
	v_mfma_f32_16x16x32_bf16 v[78:81], v[156:159], v[204:207], 0
	v_mfma_f32_16x16x32_bf16 v[126:129], v[152:155], v[184:187], v[126:129]
	v_mfma_f32_16x16x32_bf16 v[122:125], v[160:163], v[184:187], v[122:125]
	v_mfma_f32_16x16x32_bf16 v[118:121], v[152:155], v[192:195], v[118:121]
	v_mfma_f32_16x16x32_bf16 v[110:113], v[160:163], v[192:195], v[110:113]
	v_mfma_f32_16x16x32_bf16 v[102:105], v[152:155], v[200:203], v[102:105]
	v_mfma_f32_16x16x32_bf16 v[94:97], v[160:163], v[200:203], v[94:97]
	v_mfma_f32_16x16x32_bf16 v[86:89], v[152:155], v[208:211], v[86:89]
	v_mfma_f32_16x16x32_bf16 v[78:81], v[160:163], v[208:211], v[78:81]
	s_setprio 0
	s_setprio 1
	v_mfma_f32_16x16x32_bf16 v[114:117], v[164:167], v[180:183], 0
	v_mfma_f32_16x16x32_bf16 v[106:109], v[172:175], v[180:183], 0
	v_mfma_f32_16x16x32_bf16 v[98:101], v[164:167], v[188:191], 0
	v_mfma_f32_16x16x32_bf16 v[90:93], v[172:175], v[188:191], 0
	v_mfma_f32_16x16x32_bf16 v[82:85], v[164:167], v[196:199], 0
	v_mfma_f32_16x16x32_bf16 v[74:77], v[172:175], v[196:199], 0
	v_mfma_f32_16x16x32_bf16 v[70:73], v[164:167], v[204:207], 0
	v_mfma_f32_16x16x32_bf16 v[66:69], v[172:175], v[204:207], 0
	v_mfma_f32_16x16x32_bf16 v[114:117], v[168:171], v[184:187], v[114:117]
	v_mfma_f32_16x16x32_bf16 v[106:109], v[176:179], v[184:187], v[106:109]
	v_mfma_f32_16x16x32_bf16 v[98:101], v[168:171], v[192:195], v[98:101]
	v_mfma_f32_16x16x32_bf16 v[90:93], v[176:179], v[192:195], v[90:93]
	v_mfma_f32_16x16x32_bf16 v[82:85], v[168:171], v[200:203], v[82:85]
	v_mfma_f32_16x16x32_bf16 v[74:77], v[176:179], v[200:203], v[74:77]
	v_mfma_f32_16x16x32_bf16 v[70:73], v[168:171], v[208:211], v[70:73]
	v_mfma_f32_16x16x32_bf16 v[66:69], v[176:179], v[208:211], v[66:69]
	s_setprio 0
	s_barrier
	s_add_i32 s23, s23, s3
	v_lshl_add_u64 v[144:145], s[34:35], 0, v[0:1]
	s_mov_b32 m0, s23
	ds_read_b128 v[180:183], v147 offset:16384
	ds_read_b128 v[184:187], v147 offset:17408
	ds_read_b128 v[188:191], v147 offset:18432
	ds_read_b128 v[192:195], v147 offset:19456
	ds_read_b128 v[196:199], v147 offset:20480
	ds_read_b128 v[200:203], v147 offset:21504
	ds_read_b128 v[204:207], v147 offset:22528
	ds_read_b128 v[208:211], v147 offset:23552
	global_load_lds_dwordx4 v[144:145], off
	s_add_i32 m0, s23, 0x2000
	s_add_u32 s28, s34, 0x40000
	v_lshl_add_u64 v[212:213], s[34:35], 0, v[130:131]
	s_addc_u32 s29, s35, 0
	s_add_i32 s23, s56, s3
	global_load_lds_dwordx4 v[212:213], off
	v_lshl_add_u64 v[214:215], s[28:29], 0, v[0:1]
	s_mov_b32 m0, s23
	v_lshl_add_u64 v[216:217], s[36:37], 0, v[134:135]
	global_load_lds_dwordx4 v[214:215], off
	v_lshl_add_u64 v[214:215], s[28:29], 0, v[130:131]
	s_add_i32 m0, s23, 0x2000
	s_nop 0
	global_load_lds_dwordx4 v[214:215], off
	v_lshl_add_u64 v[214:215], s[36:37], 0, v[132:133]
	s_mov_b32 m0, s51
	s_nop 0
	global_load_lds_dwordx4 v[214:215], off
	s_mov_b32 m0, s52
	s_nop 0
	global_load_lds_dwordx4 v[216:217], off
	s_waitcnt vmcnt(8)
	s_waitcnt lgkmcnt(0)
	s_barrier
	s_setprio 1
	s_waitcnt lgkmcnt(0)
	v_mfma_f32_16x16x32_bf16 v[62:65], v[148:151], v[180:183], 0
	v_mfma_f32_16x16x32_bf16 v[58:61], v[156:159], v[180:183], 0
	v_mfma_f32_16x16x32_bf16 v[46:49], v[148:151], v[188:191], 0
	v_mfma_f32_16x16x32_bf16 v[38:41], v[156:159], v[188:191], 0
	v_mfma_f32_16x16x32_bf16 v[22:25], v[148:151], v[196:199], 0
	v_mfma_f32_16x16x32_bf16 v[14:17], v[156:159], v[196:199], 0
	v_mfma_f32_16x16x32_bf16 v[6:9], v[148:151], v[204:207], 0
	v_mfma_f32_16x16x32_bf16 v[2:5], v[156:159], v[204:207], 0
	v_mfma_f32_16x16x32_bf16 v[62:65], v[152:155], v[184:187], v[62:65]
	v_mfma_f32_16x16x32_bf16 v[58:61], v[160:163], v[184:187], v[58:61]
	v_mfma_f32_16x16x32_bf16 v[46:49], v[152:155], v[192:195], v[46:49]
	v_mfma_f32_16x16x32_bf16 v[38:41], v[160:163], v[192:195], v[38:41]
	v_mfma_f32_16x16x32_bf16 v[22:25], v[152:155], v[200:203], v[22:25]
	v_mfma_f32_16x16x32_bf16 v[14:17], v[160:163], v[200:203], v[14:17]
	v_mfma_f32_16x16x32_bf16 v[6:9], v[152:155], v[208:211], v[6:9]
	v_mfma_f32_16x16x32_bf16 v[2:5], v[160:163], v[208:211], v[2:5]
	s_setprio 0
	s_setprio 1
	v_mfma_f32_16x16x32_bf16 v[42:45], v[164:167], v[180:183], 0
	v_mfma_f32_16x16x32_bf16 v[34:37], v[172:175], v[180:183], 0
	v_mfma_f32_16x16x32_bf16 v[18:21], v[164:167], v[188:191], 0
	v_mfma_f32_16x16x32_bf16 v[10:13], v[172:175], v[188:191], 0
	v_mfma_f32_16x16x32_bf16 v[54:57], v[164:167], v[196:199], 0
	v_mfma_f32_16x16x32_bf16 v[50:53], v[172:175], v[196:199], 0
	v_mfma_f32_16x16x32_bf16 v[30:33], v[164:167], v[204:207], 0
	v_mfma_f32_16x16x32_bf16 v[26:29], v[172:175], v[204:207], 0
	v_mfma_f32_16x16x32_bf16 v[42:45], v[168:171], v[184:187], v[42:45]
	v_mfma_f32_16x16x32_bf16 v[34:37], v[176:179], v[184:187], v[34:37]
	v_mfma_f32_16x16x32_bf16 v[18:21], v[168:171], v[192:195], v[18:21]
	v_mfma_f32_16x16x32_bf16 v[10:13], v[176:179], v[192:195], v[10:13]
	v_mfma_f32_16x16x32_bf16 v[54:57], v[168:171], v[200:203], v[54:57]
	v_mfma_f32_16x16x32_bf16 v[50:53], v[176:179], v[200:203], v[50:53]
	v_mfma_f32_16x16x32_bf16 v[30:33], v[168:171], v[208:211], v[30:33]
	v_mfma_f32_16x16x32_bf16 v[26:29], v[176:179], v[208:211], v[26:29]
	s_setprio 0
	s_barrier
	s_add_i32 s23, 0, 0x18000
	s_add_i32 s56, 0, 0x1c000
	v_add_u32_e32 v160, s23, v146
	v_add_u32_e32 v176, s56, v146
	ds_read_b128 v[148:151], v160
	ds_read_b128 v[152:155], v160 offset:1024
	ds_read_b128 v[156:159], v160 offset:2048
	ds_read_b128 v[160:163], v160 offset:3072
	ds_read_b128 v[164:167], v176
	ds_read_b128 v[168:171], v176 offset:1024
	ds_read_b128 v[172:175], v176 offset:2048
	ds_read_b128 v[176:179], v176 offset:3072
	s_mov_b32 m0, s53
	v_lshl_add_u64 v[218:219], s[36:37], 0, v[136:137]
	ds_read_b128 v[180:183], v147 offset:32768
	ds_read_b128 v[184:187], v147 offset:33792
	ds_read_b128 v[188:191], v147 offset:34816
	ds_read_b128 v[192:195], v147 offset:35840
	ds_read_b128 v[196:199], v147 offset:36864
	ds_read_b128 v[200:203], v147 offset:37888
	ds_read_b128 v[204:207], v147 offset:38912
	ds_read_b128 v[208:211], v147 offset:39936
	global_load_lds_dwordx4 v[218:219], off
	v_lshl_add_u64 v[218:219], s[36:37], 0, v[138:139]
	s_mov_b32 m0, s54
	s_nop 0
	global_load_lds_dwordx4 v[218:219], off
	s_waitcnt vmcnt(8)
	s_waitcnt lgkmcnt(0)
	s_barrier
	s_setprio 1
	s_waitcnt lgkmcnt(0)
	v_mfma_f32_16x16x32_bf16 v[126:129], v[148:151], v[180:183], v[126:129]
	v_mfma_f32_16x16x32_bf16 v[122:125], v[156:159], v[180:183], v[122:125]
	v_mfma_f32_16x16x32_bf16 v[118:121], v[148:151], v[188:191], v[118:121]
	v_mfma_f32_16x16x32_bf16 v[110:113], v[156:159], v[188:191], v[110:113]
	v_mfma_f32_16x16x32_bf16 v[102:105], v[148:151], v[196:199], v[102:105]
	v_mfma_f32_16x16x32_bf16 v[94:97], v[156:159], v[196:199], v[94:97]
	v_mfma_f32_16x16x32_bf16 v[86:89], v[148:151], v[204:207], v[86:89]
	v_mfma_f32_16x16x32_bf16 v[78:81], v[156:159], v[204:207], v[78:81]
	v_mfma_f32_16x16x32_bf16 v[126:129], v[152:155], v[184:187], v[126:129]
	v_mfma_f32_16x16x32_bf16 v[122:125], v[160:163], v[184:187], v[122:125]
	v_mfma_f32_16x16x32_bf16 v[118:121], v[152:155], v[192:195], v[118:121]
	v_mfma_f32_16x16x32_bf16 v[110:113], v[160:163], v[192:195], v[110:113]
	v_mfma_f32_16x16x32_bf16 v[102:105], v[152:155], v[200:203], v[102:105]
	v_mfma_f32_16x16x32_bf16 v[94:97], v[160:163], v[200:203], v[94:97]
	v_mfma_f32_16x16x32_bf16 v[86:89], v[152:155], v[208:211], v[86:89]
	v_mfma_f32_16x16x32_bf16 v[78:81], v[160:163], v[208:211], v[78:81]
	s_setprio 0
	s_setprio 1
	v_mfma_f32_16x16x32_bf16 v[114:117], v[164:167], v[180:183], v[114:117]
	v_mfma_f32_16x16x32_bf16 v[106:109], v[172:175], v[180:183], v[106:109]
	v_mfma_f32_16x16x32_bf16 v[98:101], v[164:167], v[188:191], v[98:101]
	v_mfma_f32_16x16x32_bf16 v[90:93], v[172:175], v[188:191], v[90:93]
	v_mfma_f32_16x16x32_bf16 v[82:85], v[164:167], v[196:199], v[82:85]
	v_mfma_f32_16x16x32_bf16 v[74:77], v[172:175], v[196:199], v[74:77]
	v_mfma_f32_16x16x32_bf16 v[70:73], v[164:167], v[204:207], v[70:73]
	v_mfma_f32_16x16x32_bf16 v[66:69], v[172:175], v[204:207], v[66:69]
	v_mfma_f32_16x16x32_bf16 v[114:117], v[168:171], v[184:187], v[114:117]
	v_mfma_f32_16x16x32_bf16 v[106:109], v[176:179], v[184:187], v[106:109]
	v_mfma_f32_16x16x32_bf16 v[98:101], v[168:171], v[192:195], v[98:101]
	v_mfma_f32_16x16x32_bf16 v[90:93], v[176:179], v[192:195], v[90:93]
	v_mfma_f32_16x16x32_bf16 v[82:85], v[168:171], v[200:203], v[82:85]
	v_mfma_f32_16x16x32_bf16 v[74:77], v[176:179], v[200:203], v[74:77]
	v_mfma_f32_16x16x32_bf16 v[70:73], v[168:171], v[208:211], v[70:73]
	v_mfma_f32_16x16x32_bf16 v[66:69], v[176:179], v[208:211], v[66:69]
	s_setprio 0
	s_barrier
	s_add_i32 s23, s23, s3
	v_lshl_add_u64 v[144:145], v[144:145], 0, s[82:83]
	s_mov_b32 m0, s23
	ds_read_b128 v[180:183], v147 offset:49152
	ds_read_b128 v[184:187], v147 offset:50176
	ds_read_b128 v[188:191], v147 offset:51200
	ds_read_b128 v[192:195], v147 offset:52224
	ds_read_b128 v[196:199], v147 offset:53248
	ds_read_b128 v[200:203], v147 offset:54272
	ds_read_b128 v[204:207], v147 offset:55296
	ds_read_b128 v[208:211], v147 offset:56320
	global_load_lds_dwordx4 v[144:145], off
	s_add_i32 m0, s23, 0x2000
	s_add_u32 s28, s34, 0x40080
	v_lshl_add_u64 v[144:145], v[212:213], 0, s[82:83]
	s_addc_u32 s29, s35, 0
	s_add_i32 s23, s56, s3
	global_load_lds_dwordx4 v[144:145], off
	v_lshl_add_u64 v[144:145], s[28:29], 0, v[0:1]
	s_mov_b32 m0, s23
	s_nop 0
	global_load_lds_dwordx4 v[144:145], off
	v_lshl_add_u64 v[144:145], s[28:29], 0, v[130:131]
	s_add_i32 m0, s23, 0x2000
	s_nop 0
	global_load_lds_dwordx4 v[144:145], off
	v_lshl_add_u64 v[144:145], v[214:215], 0, s[82:83]
	s_mov_b32 m0, s55
	s_nop 0
	global_load_lds_dwordx4 v[144:145], off
	v_lshl_add_u64 v[144:145], v[216:217], 0, s[82:83]
	s_mov_b32 m0, s57
	s_nop 0
	global_load_lds_dwordx4 v[144:145], off
	s_waitcnt vmcnt(8)
	s_waitcnt lgkmcnt(0)
	s_barrier
	s_setprio 1
	s_waitcnt lgkmcnt(0)
	v_mfma_f32_16x16x32_bf16 v[62:65], v[148:151], v[180:183], v[62:65]
	v_mfma_f32_16x16x32_bf16 v[58:61], v[156:159], v[180:183], v[58:61]
	v_mfma_f32_16x16x32_bf16 v[46:49], v[148:151], v[188:191], v[46:49]
	v_mfma_f32_16x16x32_bf16 v[38:41], v[156:159], v[188:191], v[38:41]
	v_mfma_f32_16x16x32_bf16 v[22:25], v[148:151], v[196:199], v[22:25]
	v_mfma_f32_16x16x32_bf16 v[14:17], v[156:159], v[196:199], v[14:17]
	v_mfma_f32_16x16x32_bf16 v[6:9], v[148:151], v[204:207], v[6:9]
	v_mfma_f32_16x16x32_bf16 v[2:5], v[156:159], v[204:207], v[2:5]
	v_mfma_f32_16x16x32_bf16 v[62:65], v[152:155], v[184:187], v[62:65]
	v_mfma_f32_16x16x32_bf16 v[58:61], v[160:163], v[184:187], v[58:61]
	v_mfma_f32_16x16x32_bf16 v[46:49], v[152:155], v[192:195], v[46:49]
	v_mfma_f32_16x16x32_bf16 v[38:41], v[160:163], v[192:195], v[38:41]
	v_mfma_f32_16x16x32_bf16 v[22:25], v[152:155], v[200:203], v[22:25]
	v_mfma_f32_16x16x32_bf16 v[14:17], v[160:163], v[200:203], v[14:17]
	v_mfma_f32_16x16x32_bf16 v[6:9], v[152:155], v[208:211], v[6:9]
	v_mfma_f32_16x16x32_bf16 v[2:5], v[160:163], v[208:211], v[2:5]
	s_setprio 0
	s_setprio 1
	v_mfma_f32_16x16x32_bf16 v[42:45], v[164:167], v[180:183], v[42:45]
	v_mfma_f32_16x16x32_bf16 v[34:37], v[172:175], v[180:183], v[34:37]
	v_mfma_f32_16x16x32_bf16 v[18:21], v[164:167], v[188:191], v[18:21]
	v_mfma_f32_16x16x32_bf16 v[10:13], v[172:175], v[188:191], v[10:13]
	v_mfma_f32_16x16x32_bf16 v[54:57], v[164:167], v[196:199], v[54:57]
	v_mfma_f32_16x16x32_bf16 v[50:53], v[172:175], v[196:199], v[50:53]
	v_mfma_f32_16x16x32_bf16 v[30:33], v[164:167], v[204:207], v[30:33]
	v_mfma_f32_16x16x32_bf16 v[26:29], v[172:175], v[204:207], v[26:29]
	v_mfma_f32_16x16x32_bf16 v[42:45], v[168:171], v[184:187], v[42:45]
	v_mfma_f32_16x16x32_bf16 v[34:37], v[176:179], v[184:187], v[34:37]
	v_mfma_f32_16x16x32_bf16 v[18:21], v[168:171], v[192:195], v[18:21]
	v_mfma_f32_16x16x32_bf16 v[10:13], v[176:179], v[192:195], v[10:13]
	v_mfma_f32_16x16x32_bf16 v[54:57], v[168:171], v[200:203], v[54:57]
	v_mfma_f32_16x16x32_bf16 v[50:53], v[176:179], v[200:203], v[50:53]
	v_mfma_f32_16x16x32_bf16 v[30:33], v[168:171], v[208:211], v[30:33]
	v_mfma_f32_16x16x32_bf16 v[26:29], v[176:179], v[208:211], v[26:29]
	s_setprio 0
	s_barrier
	s_branch .Lpeel_latch_1552

.Lpeel_latch_1552:
	s_add_i32 s69, s69, 2
	s_add_u32 s67, s67, 0x100
	s_addc_u32 s68, s68, 0
	s_cmp_gt_u32 s69, 13
	s_mov_b64 s[28:29], s[30:31]
	s_cbranch_scc0 .LBB0_1552
	s_and_b64 vcc, exec, s[18:19]
	s_cbranch_vccz .LBB0_1555
	s_barrier
